# attention loops unrolled by two: K buffer offsets as immediates, SGPR-base global prefetch (per-tile VALU address math removed)
# speedup vs baseline: 1.0079x; 1.0079x over previous
.LBB0_610:
	s_ashr_i32 s5, s23, 7
	s_bfe_u32 s4, s23, 0x20005
	s_mul_hi_i32 s8, s5, 0x3e00000
	s_mul_i32 s5, s5, 0x3e00000
	s_add_u32 s18, s2, s5
	s_addc_u32 s19, s17, s8
	s_lshl_b32 s5, s23, 7
	s_and_b32 s5, s5, 0xf80
	v_and_b32_e32 v64, 15, v2
	v_lshl_add_u32 v0, v3, 4, s5
	v_or_b32_e32 v66, v0, v64
	v_mov_b64_e32 v[20:21], s[18:19]
	v_mad_i64_i32 v[4:5], s[18:19], v66, s65, v[20:21]
	s_lshl_b32 s8, s4, 8
	v_bfe_u32 v65, v2, 4, 2
	v_lshl_add_u64 v[4:5], v[4:5], 0, s[8:9]
	s_mov_b64 s[18:19], 0x2200
	v_lshl_add_u64 v[132:133], v[4:5], 0, s[18:19]
	v_lshlrev_b32_e32 v0, 4, v65
	v_lshl_add_u64 v[16:17], v[132:133], 0, v[0:1]
	v_ashrrev_i32_e32 v67, 4, v2
	global_load_dwordx4 v[4:7], v[16:17], off
	global_load_dwordx4 v[8:11], v[16:17], off offset:64
	global_load_dwordx4 v[12:15], v[16:17], off offset:128
	s_nop 0
	global_load_dwordx4 v[16:19], v[16:17], off offset:192
	v_lshlrev_b32_e32 v0, 4, v2
	v_mad_i64_i32 v[20:21], s[18:19], v67, s65, v[20:21]
	v_lshl_add_u64 v[20:21], v[20:21], 0, s[8:9]
	v_and_b32_e32 v0, 0xf0, v0
	v_lshl_add_u64 v[36:37], v[20:21], 0, v[0:1]
	v_add_co_u32_e32 v24, vcc, s64, v36
	s_mov_b32 s5, 0x7e000
	s_nop 0
	v_addc_co_u32_e32 v25, vcc, 0, v37, vcc
	v_add_co_u32_e32 v32, vcc, s5, v36
	s_mov_b64 s[18:19], 0x2600
	s_waitcnt lgkmcnt(0)
	v_addc_co_u32_e32 v33, vcc, 0, v37, vcc
	global_load_dwordx4 v[20:23], v[24:25], off offset:1536
	s_nop 0
	global_load_dwordx4 v[24:27], v[24:25], off offset:2560
	s_nop 0
	global_load_dwordx4 v[28:31], v[32:33], off offset:1536
	s_nop 0
	global_load_dwordx4 v[32:35], v[32:33], off offset:2560
	v_lshl_add_u64 v[134:135], v[36:37], 0, s[18:19]
	s_mov_b64 s[18:19], 0x2a00
	v_lshl_add_u64 v[136:137], v[36:37], 0, s[18:19]
	v_mul_lo_u32 v36, v67, s21
	v_add3_u32 v169, 0, v0, v36
	v_lshlrev_b32_e32 v167, 2, v65
	s_barrier
	s_not_b32 s4, s4
	s_lshl_b32 s4, s4, 1
	v_ldexp_f32 v0, 1.0, s4
	v_lshlrev_b32_e32 v68, 3, v65
	v_mul_f32_e32 v150, 0x3fb8aa3b, v0
	v_readfirstlane_b32 s4, v3
	v_mul_u32_u24_e32 v0, 0x90, v64
	s_cmp_gt_i32 s4, 3
	s_mov_b64 s[4:5], -1
	v_lshlrev_b32_e32 v171, 1, v0
	v_lshlrev_b32_e32 v172, 1, v68
	s_waitcnt vmcnt(3)
	ds_write_b128 v169, v[20:23]
	s_waitcnt vmcnt(2)
	ds_write_b128 v169, v[24:27] offset:36864
	s_waitcnt vmcnt(1)
	ds_write_b128 v169, v[28:31] offset:9216
	s_waitcnt vmcnt(0)
	ds_write_b128 v169, v[32:35] offset:46080
	v_lshlrev_b32_e32 v38, 16, v4
	v_and_b32_e32 v39, 0xffff0000, v4
	v_lshlrev_b32_e32 v4, 16, v5
	v_and_b32_e32 v5, 0xffff0000, v5
	v_lshlrev_b32_e32 v50, 16, v16
	v_and_b32_e32 v51, 0xffff0000, v16
	v_pk_mul_f32 v[38:39], v[38:39], s[16:17] op_sel_hi:[1,0]
	v_pk_mul_f32 v[52:53], v[4:5], s[16:17] op_sel_hi:[1,0]
	v_cvt_pk_bf16_f32 v4, v38, v39
	v_pk_mul_f32 v[38:39], v[50:51], s[16:17] op_sel_hi:[1,0]
	v_sub_u32_e32 v20, v167, v66
	v_cvt_pk_bf16_f32 v16, v38, v39
	v_lshlrev_b32_e32 v38, 16, v17
	v_and_b32_e32 v39, 0xffff0000, v17
	v_pk_mul_f32 v[38:39], v[38:39], s[16:17] op_sel_hi:[1,0]
	v_cvt_f32_i32_e32 v170, v20
	v_cvt_pk_bf16_f32 v17, v38, v39
	v_lshlrev_b32_e32 v38, 16, v18
	v_and_b32_e32 v39, 0xffff0000, v18
	v_pk_mul_f32 v[38:39], v[38:39], s[16:17] op_sel_hi:[1,0]
	v_lshlrev_b32_e32 v40, 16, v6
	v_cvt_pk_bf16_f32 v18, v38, v39
	v_lshlrev_b32_e32 v38, 16, v19
	v_and_b32_e32 v39, 0xffff0000, v19
	v_pk_mul_f32 v[38:39], v[38:39], s[16:17] op_sel_hi:[1,0]
	v_and_b32_e32 v41, 0xffff0000, v6
	v_cvt_pk_bf16_f32 v19, v38, v39
	v_lshlrev_b32_e32 v38, 3, v2
	v_bfe_u32 v2, v2, 2, 2
	v_lshlrev_b32_e32 v6, 16, v7
	v_and_b32_e32 v7, 0xffff0000, v7
	v_lshlrev_b32_e32 v42, 16, v8
	v_and_b32_e32 v43, 0xffff0000, v8
	v_lshlrev_b32_e32 v8, 16, v9
	v_and_b32_e32 v9, 0xffff0000, v9
	v_lshlrev_b32_e32 v44, 16, v10
	v_and_b32_e32 v45, 0xffff0000, v10
	v_lshlrev_b32_e32 v10, 16, v11
	v_and_b32_e32 v11, 0xffff0000, v11
	v_lshlrev_b32_e32 v46, 16, v12
	v_and_b32_e32 v47, 0xffff0000, v12
	v_lshlrev_b32_e32 v12, 16, v13
	v_and_b32_e32 v13, 0xffff0000, v13
	v_lshlrev_b32_e32 v48, 16, v14
	v_and_b32_e32 v49, 0xffff0000, v14
	v_lshlrev_b32_e32 v14, 16, v15
	v_and_b32_e32 v15, 0xffff0000, v15
	v_or_b32_e32 v2, v167, v2
	v_pk_mul_f32 v[40:41], v[40:41], s[16:17] op_sel_hi:[1,0]
	v_pk_mul_f32 v[54:55], v[6:7], s[16:17] op_sel_hi:[1,0]
	v_pk_mul_f32 v[42:43], v[42:43], s[16:17] op_sel_hi:[1,0]
	v_pk_mul_f32 v[56:57], v[8:9], s[16:17] op_sel_hi:[1,0]
	v_pk_mul_f32 v[44:45], v[44:45], s[16:17] op_sel_hi:[1,0]
	v_pk_mul_f32 v[58:59], v[10:11], s[16:17] op_sel_hi:[1,0]
	v_pk_mul_f32 v[46:47], v[46:47], s[16:17] op_sel_hi:[1,0]
	v_pk_mul_f32 v[60:61], v[12:13], s[16:17] op_sel_hi:[1,0]
	v_pk_mul_f32 v[48:49], v[48:49], s[16:17] op_sel_hi:[1,0]
	v_pk_mul_f32 v[62:63], v[14:15], s[16:17] op_sel_hi:[1,0]
	v_and_b32_e32 v3, 24, v38
	v_mad_u32_u24 v2, v2, s21, 0
	v_cvt_pk_bf16_f32 v5, v52, v53
	v_cvt_pk_bf16_f32 v6, v40, v41
	v_cvt_pk_bf16_f32 v7, v54, v55
	v_cvt_pk_bf16_f32 v8, v42, v43
	v_cvt_pk_bf16_f32 v9, v56, v57
	v_cvt_pk_bf16_f32 v10, v44, v45
	v_cvt_pk_bf16_f32 v11, v58, v59
	v_cvt_pk_bf16_f32 v12, v46, v47
	v_cvt_pk_bf16_f32 v13, v60, v61
	v_cvt_pk_bf16_f32 v14, v48, v49
	v_cvt_pk_bf16_f32 v15, v62, v63
	v_add_u32_e32 v168, v2, v3
	s_waitcnt lgkmcnt(0)
	s_barrier
	s_cbranch_scc0 .Ld_groupA
	v_mov_b32_e32 v28, 0
	v_mov_b32_e32 v29, 0
	v_mov_b32_e32 v30, 0
	v_mov_b32_e32 v31, 0
	v_mov_b32_e32 v32, 0
	v_mov_b32_e32 v33, 0
	v_mov_b32_e32 v34, 0
	v_mov_b32_e32 v35, 0
	v_mov_b32_e32 v40, 0
	v_mov_b32_e32 v41, 0
	v_mov_b32_e32 v42, 0
	v_mov_b32_e32 v43, 0
	v_mov_b32_e32 v52, 0
	v_mov_b32_e32 v53, 0
	v_mov_b32_e32 v54, 0
	v_mov_b32_e32 v55, 0
	v_mov_b32_e32 v56, 0
	v_mov_b32_e32 v57, 0
	v_mov_b32_e32 v58, 0
	v_mov_b32_e32 v59, 0
	v_mov_b32_e32 v64, 0
	v_mov_b32_e32 v65, 0
	v_mov_b32_e32 v66, 0
	v_mov_b32_e32 v67, 0
	v_mov_b32_e32 v72, 0
	v_mov_b32_e32 v73, 0
	v_mov_b32_e32 v74, 0
	v_mov_b32_e32 v75, 0
	v_mov_b32_e32 v84, 0
	v_mov_b32_e32 v85, 0
	v_mov_b32_e32 v86, 0
	v_mov_b32_e32 v87, 0
	v_mov_b32_e32 v36, 0
	v_mov_b32_e32 v37, 0
	v_mov_b32_e32 v38, 0
	v_mov_b32_e32 v39, 0
	v_mov_b32_e32 v44, 0
	v_mov_b32_e32 v45, 0
	v_mov_b32_e32 v46, 0
	v_mov_b32_e32 v47, 0
	v_mov_b32_e32 v48, 0
	v_mov_b32_e32 v49, 0
	v_mov_b32_e32 v50, 0
	v_mov_b32_e32 v51, 0
	v_mov_b32_e32 v60, 0
	v_mov_b32_e32 v61, 0
	v_mov_b32_e32 v62, 0
	v_mov_b32_e32 v63, 0
	v_mov_b32_e32 v68, 0
	v_mov_b32_e32 v69, 0
	v_mov_b32_e32 v70, 0
	v_mov_b32_e32 v71, 0
	v_mov_b32_e32 v76, 0
	v_mov_b32_e32 v77, 0
	v_mov_b32_e32 v78, 0
	v_mov_b32_e32 v79, 0
	v_mov_b32_e32 v80, 0
	v_mov_b32_e32 v81, 0
	v_mov_b32_e32 v82, 0
	v_mov_b32_e32 v83, 0
	v_mov_b32_e32 v20, 0
	v_mov_b32_e32 v21, 0
	v_mov_b32_e32 v22, 0
	v_mov_b32_e32 v23, 0
	v_mov_b32_e32 v120, 0
	v_mov_b32_e32 v121, 0
	v_mov_b32_e32 v122, 0
	v_mov_b32_e32 v123, 0
	v_mov_b32_e32 v124, 0
	v_mov_b32_e32 v125, 0
	v_mov_b32_e32 v126, 0
	v_mov_b32_e32 v127, 0
	v_mov_b32_e32 v128, 0
	v_mov_b32_e32 v129, 0
	v_mov_b32_e32 v130, 0
	v_mov_b32_e32 v131, 0
	v_mov_b32_e32 v152, 0
	v_mov_b32_e32 v153, 0
	v_mov_b32_e32 v154, 0
	v_mov_b32_e32 v155, 0
	v_mov_b32_e32 v0, 0
	v_mov_b32_e32 v151, 0
	v_mov_b32_e32 v24, 0
	v_mov_b32_e32 v25, 0
	s_mov_b32 s66, 0xff800000
	v_add_u32_e32 v255, v171, v172
	v_mov_b32_e32 v165, v170
	v_readfirstlane_b32 s42, v134
	v_readfirstlane_b32 s43, v135
	v_readfirstlane_b32 s46, v136
	v_readfirstlane_b32 s47, v137
	s_nop 3
	v_subrev_u32_e32 v173, s42, v134
	v_subrev_u32_e32 v175, s46, v136
	s_mov_b32 s5, 0
	s_mov_b32 s31, 0
	s_mov_b32 s38, 0
	s_mov_b32 s39, 0x4800
	s_mov_b32 s30, 0xf8000
	v_mov_b32_e32 v88, 0xff800000
	v_mov_b32_e32 v89, 0xff800000
	v_mov_b32_e32 v90, 0xff800000
	v_mov_b32_e32 v91, 0xff800000
	v_mov_b32_e32 v92, 0xff800000
	v_mov_b32_e32 v93, 0xff800000
	v_mov_b32_e32 v94, 0xff800000
	v_mov_b32_e32 v95, 0xff800000
	v_mov_b32_e32 v96, 0xff800000
	v_mov_b32_e32 v97, 0xff800000
	v_mov_b32_e32 v98, 0xff800000
	v_mov_b32_e32 v99, 0xff800000
	v_mov_b32_e32 v100, 0xff800000
	v_mov_b32_e32 v101, 0xff800000
	v_mov_b32_e32 v102, 0xff800000
	v_mov_b32_e32 v103, 0xff800000
	v_mov_b32_e32 v104, 0xff800000
	v_mov_b32_e32 v105, 0xff800000
	v_mov_b32_e32 v106, 0xff800000
	v_mov_b32_e32 v107, 0xff800000
	v_mov_b32_e32 v108, 0xff800000
	v_mov_b32_e32 v109, 0xff800000
	v_mov_b32_e32 v110, 0xff800000
	v_mov_b32_e32 v111, 0xff800000
	v_mov_b32_e32 v112, 0xff800000
	v_mov_b32_e32 v113, 0xff800000
	v_mov_b32_e32 v114, 0xff800000
	v_mov_b32_e32 v115, 0xff800000
	v_mov_b32_e32 v116, 0xff800000
	v_mov_b32_e32 v117, 0xff800000
	v_mov_b32_e32 v118, 0xff800000
	v_mov_b32_e32 v119, 0xff800000
.Ld_loopB:
	v_add_u32_e32 v174, s31, v168
	v_add_u32_e32 v164, s39, v169
	s_add_u32 s80, s42, s30
	s_addc_u32 s81, s43, 0
	s_add_u32 s86, s80, 0x7c000
	s_addc_u32 s87, s81, 0
	s_add_u32 s96, s46, s30
	s_addc_u32 s97, s47, 0
	s_add_u32 s98, s96, 0x7c000
	s_addc_u32 s99, s97, 0
	global_load_dwordx4 v[212:215], v173, s[80:81]
	global_load_dwordx4 v[220:223], v175, s[96:97]
	global_load_dwordx4 v[216:219], v173, s[86:87]
	global_load_dwordx4 v[224:227], v175, s[98:99]
	ds_read_b128 v[228:231], v255 offset:0
	ds_read_b128 v[232:235], v255 offset:64
	ds_read_b128 v[236:239], v255 offset:4608
	ds_read_b128 v[240:243], v255 offset:4672
	v_max3_f32 v26, v88, v89, v90
	v_max3_f32 v26, v26, v91, v92
	v_max3_f32 v26, v26, v93, v94
	v_max3_f32 v26, v26, v95, v96
	v_max3_f32 v26, v26, v97, v98
	v_max3_f32 v26, v26, v99, v100
	v_max3_f32 v26, v26, v101, v102
	v_max_f32_e32 v26, v26, v103
	v_cmp_lt_f32_e32 vcc, s66, v26
	s_cbranch_vccz .Ld_nr_B0_0
	v_mov_b32_e32 v27, v26
	s_nop 1
	v_permlane16_swap_b32_e32 v26, v27
	v_max_f32_e32 v26, v26, v27
	v_mov_b32_e32 v27, v26
	s_nop 1
	v_permlane32_swap_b32_e32 v26, v27
	v_max_f32_e32 v26, v26, v27
	v_cmp_lt_f32_e32 vcc, s66, v26
	s_nop 1
	v_cndmask_b32_e32 v3, 0, v26, vcc
	v_sub_f32_e32 v2, 0, v3
	v_min_f32_e32 v2, 0, v2
	v_exp_f32_e32 v2, v2
	v_sub_f32_e32 v24, v24, v3
	v_mul_f32_e32 v0, v0, v2
	v_mul_f32_e32 v28, v28, v2
	v_mul_f32_e32 v29, v29, v2
	v_mul_f32_e32 v30, v30, v2
	v_mul_f32_e32 v31, v31, v2
	v_mul_f32_e32 v32, v32, v2
	v_mul_f32_e32 v33, v33, v2
	v_mul_f32_e32 v34, v34, v2
	v_mul_f32_e32 v35, v35, v2
	v_mul_f32_e32 v40, v40, v2
	v_mul_f32_e32 v41, v41, v2
	v_mul_f32_e32 v42, v42, v2
	v_mul_f32_e32 v43, v43, v2
	v_mul_f32_e32 v52, v52, v2
	v_mul_f32_e32 v53, v53, v2
	v_mul_f32_e32 v54, v54, v2
	v_mul_f32_e32 v55, v55, v2
	v_mul_f32_e32 v56, v56, v2
	v_mul_f32_e32 v57, v57, v2
	v_mul_f32_e32 v58, v58, v2
	v_mul_f32_e32 v59, v59, v2
	v_mul_f32_e32 v64, v64, v2
	v_mul_f32_e32 v65, v65, v2
	v_mul_f32_e32 v66, v66, v2
	v_mul_f32_e32 v67, v67, v2
	v_mul_f32_e32 v72, v72, v2
	v_mul_f32_e32 v73, v73, v2
	v_mul_f32_e32 v74, v74, v2
	v_mul_f32_e32 v75, v75, v2
	v_mul_f32_e32 v84, v84, v2
	v_mul_f32_e32 v85, v85, v2
	v_mul_f32_e32 v86, v86, v2
	v_mul_f32_e32 v87, v87, v2
	v_sub_f32_e32 v88, v88, v3
	v_sub_f32_e32 v89, v89, v3
	v_sub_f32_e32 v90, v90, v3
	v_sub_f32_e32 v91, v91, v3
	v_sub_f32_e32 v92, v92, v3
	v_sub_f32_e32 v93, v93, v3
	v_sub_f32_e32 v94, v94, v3
	v_sub_f32_e32 v95, v95, v3
	v_sub_f32_e32 v96, v96, v3
	v_sub_f32_e32 v97, v97, v3
	v_sub_f32_e32 v98, v98, v3
	v_sub_f32_e32 v99, v99, v3
	v_sub_f32_e32 v100, v100, v3
	v_sub_f32_e32 v101, v101, v3
	v_sub_f32_e32 v102, v102, v3
	v_sub_f32_e32 v103, v103, v3

.Ld_nr_B0_1:
	v_exp_f32_e32 v104, v104
	v_exp_f32_e32 v105, v105
	v_exp_f32_e32 v106, v106
	v_exp_f32_e32 v107, v107
	v_exp_f32_e32 v108, v108
	v_exp_f32_e32 v109, v109
	v_exp_f32_e32 v110, v110
	v_exp_f32_e32 v111, v111
	v_exp_f32_e32 v112, v112
	v_exp_f32_e32 v113, v113
	v_exp_f32_e32 v114, v114
	v_exp_f32_e32 v115, v115
	v_exp_f32_e32 v116, v116
	v_exp_f32_e32 v117, v117
	v_exp_f32_e32 v118, v118
	v_exp_f32_e32 v119, v119
	s_nop 0
	v_add_f32_e32 v26, v104, v105
	v_add_f32_e32 v26, v26, v106
	v_add_f32_e32 v26, v26, v107
	v_add_f32_e32 v26, v26, v108
	v_add_f32_e32 v26, v26, v109
	v_add_f32_e32 v26, v26, v110
	v_add_f32_e32 v26, v26, v111
	v_add_f32_e32 v26, v26, v112
	v_add_f32_e32 v26, v26, v113
	v_add_f32_e32 v26, v26, v114
	v_add_f32_e32 v26, v26, v115
	v_add_f32_e32 v26, v26, v116
	v_add_f32_e32 v26, v26, v117
	v_add_f32_e32 v26, v26, v118
	v_add_f32_e32 v26, v26, v119
	v_add_f32_e32 v151, v151, v26
	v_cvt_pk_bf16_f32 v128, v104, v105
	v_cvt_pk_bf16_f32 v129, v106, v107
	v_cvt_pk_bf16_f32 v130, v108, v109
	v_cvt_pk_bf16_f32 v131, v110, v111
	v_cvt_pk_bf16_f32 v152, v112, v113
	v_cvt_pk_bf16_f32 v153, v114, v115
	v_cvt_pk_bf16_f32 v154, v116, v117
	v_cvt_pk_bf16_f32 v155, v118, v119
	v_mov_b32_e32 v156, v165
	v_add_f32_e32 v157, 0x3f800000, v165
	v_add_f32_e32 v158, 0x40000000, v165
	v_add_f32_e32 v159, 0x40400000, v165
	v_add_f32_e32 v160, 0x41800000, v165
	v_add_f32_e32 v161, 0x41880000, v165
	v_add_f32_e32 v162, 0x41900000, v165
	v_add_f32_e32 v163, 0x41980000, v165
	v_add_f32_e32 v176, 0x42000000, v165
	v_add_f32_e32 v177, 0x42040000, v165
	v_add_f32_e32 v178, 0x42080000, v165
	v_add_f32_e32 v179, 0x420c0000, v165
	v_add_f32_e32 v180, 0x42400000, v165
	v_add_f32_e32 v181, 0x42440000, v165
	v_add_f32_e32 v182, 0x42480000, v165
	v_add_f32_e32 v183, 0x424c0000, v165
	v_fma_f32 v204, -v150, |v156|, v25
	v_fma_f32 v205, -v150, |v157|, v25
	v_fma_f32 v206, -v150, |v158|, v25
	v_fma_f32 v207, -v150, |v159|, v25
	v_fma_f32 v208, -v150, |v160|, v25
	v_fma_f32 v209, -v150, |v161|, v25
	v_fma_f32 v210, -v150, |v162|, v25
	v_fma_f32 v211, -v150, |v163|, v25
	v_fma_f32 v184, -v150, |v176|, v25
	v_fma_f32 v185, -v150, |v177|, v25
	v_fma_f32 v186, -v150, |v178|, v25
	v_fma_f32 v187, -v150, |v179|, v25
	v_fma_f32 v188, -v150, |v180|, v25
	v_fma_f32 v189, -v150, |v181|, v25
	v_fma_f32 v190, -v150, |v182|, v25
	v_fma_f32 v191, -v150, |v183|, v25
	v_fma_f32 v156, -v150, |v156|, v24
	v_fma_f32 v157, -v150, |v157|, v24
	v_fma_f32 v158, -v150, |v158|, v24
	v_fma_f32 v159, -v150, |v159|, v24
	v_fma_f32 v160, -v150, |v160|, v24
	v_fma_f32 v161, -v150, |v161|, v24
	v_fma_f32 v162, -v150, |v162|, v24
	v_fma_f32 v163, -v150, |v163|, v24
	v_fma_f32 v176, -v150, |v176|, v24
	v_fma_f32 v177, -v150, |v177|, v24
	v_fma_f32 v178, -v150, |v178|, v24
	v_fma_f32 v179, -v150, |v179|, v24
	v_fma_f32 v180, -v150, |v180|, v24
	v_fma_f32 v181, -v150, |v181|, v24
	v_fma_f32 v182, -v150, |v182|, v24
	v_fma_f32 v183, -v150, |v183|, v24
	ds_read_b128 v[244:247], v255 offset:9216
	s_waitcnt lgkmcnt(4)
	v_mfma_f32_16x16x32_bf16 v[88:91], v[228:231], v[4:7], v[156:159]
	ds_read_b128 v[248:251], v255 offset:9280
	s_waitcnt lgkmcnt(4)
	v_mfma_f32_16x16x32_bf16 v[88:91], v[232:235], v[8:11], v[88:91]
	ds_read_b128 v[228:231], v255 offset:13824
	s_waitcnt lgkmcnt(4)
	v_mfma_f32_16x16x32_bf16 v[92:95], v[236:239], v[4:7], v[160:163]
	ds_read_b128 v[232:235], v255 offset:13888
	s_waitcnt lgkmcnt(4)
	v_mfma_f32_16x16x32_bf16 v[92:95], v[240:243], v[8:11], v[92:95]
	ds_read_b128 v[236:239], v255 offset:128
	s_waitcnt lgkmcnt(4)
	v_mfma_f32_16x16x32_bf16 v[96:99], v[244:247], v[4:7], v[176:179]
	ds_read_b128 v[240:243], v255 offset:192
	s_waitcnt lgkmcnt(4)
	v_mfma_f32_16x16x32_bf16 v[96:99], v[248:251], v[8:11], v[96:99]
	ds_read_b128 v[244:247], v255 offset:4736
	s_waitcnt lgkmcnt(4)
	v_mfma_f32_16x16x32_bf16 v[100:103], v[228:231], v[4:7], v[180:183]
	ds_read_b128 v[248:251], v255 offset:4800
	s_waitcnt lgkmcnt(4)
	v_mfma_f32_16x16x32_bf16 v[100:103], v[232:235], v[8:11], v[100:103]
	ds_read_b128 v[228:231], v255 offset:9344
	s_waitcnt lgkmcnt(4)
	v_mfma_f32_16x16x32_bf16 v[104:107], v[236:239], v[12:15], v[204:207]
	ds_read_b128 v[232:235], v255 offset:9408
	s_waitcnt lgkmcnt(4)
	v_mfma_f32_16x16x32_bf16 v[104:107], v[240:243], v[16:19], v[104:107]
	ds_read_b128 v[236:239], v255 offset:13952
	s_waitcnt lgkmcnt(4)
	v_mfma_f32_16x16x32_bf16 v[108:111], v[244:247], v[12:15], v[208:211]
	ds_read_b128 v[240:243], v255 offset:14016
	s_waitcnt lgkmcnt(4)
	v_mfma_f32_16x16x32_bf16 v[108:111], v[248:251], v[16:19], v[108:111]
	ds_read_b64_tr_b16 v[244:245], v174 offset:36864
	ds_read_b64_tr_b16 v[246:247], v174 offset:41472
	s_waitcnt lgkmcnt(5)
	v_mfma_f32_16x16x32_bf16 v[112:115], v[228:231], v[12:15], v[184:187]
	ds_read_b64_tr_b16 v[248:249], v174 offset:36896
	ds_read_b64_tr_b16 v[250:251], v174 offset:41504
	s_waitcnt lgkmcnt(6)
	v_mfma_f32_16x16x32_bf16 v[112:115], v[232:235], v[16:19], v[112:115]
	ds_read_b64_tr_b16 v[228:229], v174 offset:36928
	ds_read_b64_tr_b16 v[230:231], v174 offset:41536
	s_waitcnt lgkmcnt(7)
	v_mfma_f32_16x16x32_bf16 v[116:119], v[236:239], v[12:15], v[188:191]
	ds_read_b64_tr_b16 v[232:233], v174 offset:36960
	ds_read_b64_tr_b16 v[234:235], v174 offset:41568
	s_waitcnt lgkmcnt(8)
	v_mfma_f32_16x16x32_bf16 v[116:119], v[240:243], v[16:19], v[116:119]
	ds_read_b64_tr_b16 v[236:237], v174 offset:36992
	ds_read_b64_tr_b16 v[238:239], v174 offset:41600
	s_waitcnt lgkmcnt(8)
	v_mfma_f32_16x16x32_bf16 v[28:31], v[244:247], v[120:123], v[28:31]
	v_mfma_f32_16x16x32_bf16 v[36:39], v[244:247], v[128:131], v[36:39]
	ds_read_b64_tr_b16 v[240:241], v174 offset:37024
	ds_read_b64_tr_b16 v[242:243], v174 offset:41632
	s_waitcnt lgkmcnt(8)
	v_mfma_f32_16x16x32_bf16 v[32:35], v[248:251], v[120:123], v[32:35]
	v_mfma_f32_16x16x32_bf16 v[44:47], v[248:251], v[128:131], v[44:47]
	ds_read_b64_tr_b16 v[244:245], v174 offset:37056
	ds_read_b64_tr_b16 v[246:247], v174 offset:41664
	s_waitcnt lgkmcnt(8)
	v_mfma_f32_16x16x32_bf16 v[40:43], v[228:231], v[120:123], v[40:43]
	v_mfma_f32_16x16x32_bf16 v[48:51], v[228:231], v[128:131], v[48:51]
	ds_read_b64_tr_b16 v[248:249], v174 offset:37088
	ds_read_b64_tr_b16 v[250:251], v174 offset:41696
	s_waitcnt lgkmcnt(8)
	v_mfma_f32_16x16x32_bf16 v[52:55], v[232:235], v[120:123], v[52:55]
	v_mfma_f32_16x16x32_bf16 v[60:63], v[232:235], v[128:131], v[60:63]
	ds_read_b64_tr_b16 v[228:229], v174 offset:46080
	ds_read_b64_tr_b16 v[230:231], v174 offset:50688
	s_waitcnt lgkmcnt(8)
	v_mfma_f32_16x16x32_bf16 v[56:59], v[236:239], v[120:123], v[56:59]
	v_mfma_f32_16x16x32_bf16 v[68:71], v[236:239], v[128:131], v[68:71]
	ds_read_b64_tr_b16 v[232:233], v174 offset:46112
	ds_read_b64_tr_b16 v[234:235], v174 offset:50720
	s_waitcnt lgkmcnt(8)
	v_mfma_f32_16x16x32_bf16 v[64:67], v[240:243], v[120:123], v[64:67]
	v_mfma_f32_16x16x32_bf16 v[76:79], v[240:243], v[128:131], v[76:79]
	ds_read_b64_tr_b16 v[236:237], v174 offset:46144
	ds_read_b64_tr_b16 v[238:239], v174 offset:50752
	s_waitcnt lgkmcnt(8)
	v_mfma_f32_16x16x32_bf16 v[72:75], v[244:247], v[120:123], v[72:75]
	v_mfma_f32_16x16x32_bf16 v[80:83], v[244:247], v[128:131], v[80:83]
	ds_read_b64_tr_b16 v[240:241], v174 offset:46176
	ds_read_b64_tr_b16 v[242:243], v174 offset:50784
	s_waitcnt lgkmcnt(8)
	v_mfma_f32_16x16x32_bf16 v[84:87], v[248:251], v[120:123], v[84:87]
	v_mfma_f32_16x16x32_bf16 v[20:23], v[248:251], v[128:131], v[20:23]
	ds_read_b64_tr_b16 v[244:245], v174 offset:46208
	ds_read_b64_tr_b16 v[246:247], v174 offset:50816
	s_waitcnt lgkmcnt(8)
	v_mfma_f32_16x16x32_bf16 v[28:31], v[228:231], v[124:127], v[28:31]
	v_mfma_f32_16x16x32_bf16 v[36:39], v[228:231], v[152:155], v[36:39]
	ds_read_b64_tr_b16 v[248:249], v174 offset:46240
	ds_read_b64_tr_b16 v[250:251], v174 offset:50848
	s_waitcnt lgkmcnt(8)
	v_mfma_f32_16x16x32_bf16 v[32:35], v[232:235], v[124:127], v[32:35]
	v_mfma_f32_16x16x32_bf16 v[44:47], v[232:235], v[152:155], v[44:47]
	ds_read_b64_tr_b16 v[228:229], v174 offset:46272
	ds_read_b64_tr_b16 v[230:231], v174 offset:50880
	s_waitcnt lgkmcnt(8)
	v_mfma_f32_16x16x32_bf16 v[40:43], v[236:239], v[124:127], v[40:43]
	v_mfma_f32_16x16x32_bf16 v[48:51], v[236:239], v[152:155], v[48:51]
	ds_read_b64_tr_b16 v[232:233], v174 offset:46304
	ds_read_b64_tr_b16 v[234:235], v174 offset:50912
	s_waitcnt lgkmcnt(8)
	v_mfma_f32_16x16x32_bf16 v[52:55], v[240:243], v[124:127], v[52:55]
	v_mfma_f32_16x16x32_bf16 v[60:63], v[240:243], v[152:155], v[60:63]
	s_waitcnt lgkmcnt(6)
	v_mfma_f32_16x16x32_bf16 v[56:59], v[244:247], v[124:127], v[56:59]
	v_mfma_f32_16x16x32_bf16 v[68:71], v[244:247], v[152:155], v[68:71]
	s_waitcnt lgkmcnt(4)
	v_mfma_f32_16x16x32_bf16 v[64:67], v[248:251], v[124:127], v[64:67]
	v_mfma_f32_16x16x32_bf16 v[76:79], v[248:251], v[152:155], v[76:79]
	s_waitcnt lgkmcnt(2)
	v_mfma_f32_16x16x32_bf16 v[72:75], v[228:231], v[124:127], v[72:75]
	v_mfma_f32_16x16x32_bf16 v[80:83], v[228:231], v[152:155], v[80:83]
	s_waitcnt lgkmcnt(0)
	v_mfma_f32_16x16x32_bf16 v[84:87], v[232:235], v[124:127], v[84:87]
	v_mfma_f32_16x16x32_bf16 v[20:23], v[232:235], v[152:155], v[20:23]
	s_waitcnt vmcnt(0)
	ds_write_b128 v169, v[212:215] offset:18432
	ds_write_b128 v169, v[216:219] offset:27648
	ds_write_b128 v164, v[220:223] offset:36864
	ds_write_b128 v164, v[224:227] offset:46080
	s_mov_b32 s31, s38
	s_mov_b32 s38, s39
	s_add_i32 s39, s39, 0x4800
	s_cmp_lg_u32 s39, 0xd800
	s_cselect_b32 s39, s39, 0
	s_mov_b32 s66, 0xff800000
	s_cmp_ge_u32 s5, 1
	s_cselect_b32 s66, 0x42800000, s66
	s_add_i32 s5, s5, 1
	s_min_u32 s8, s5, 62
	s_add_i32 s8, s8, 1
	s_mul_i32 s30, s8, 0xf8000
	v_add_f32_e32 v165, 0x42800000, v165
	s_waitcnt lgkmcnt(0)
	s_barrier
	v_add_u32_e32 v174, s31, v168
	v_add_u32_e32 v164, s39, v169
	s_add_u32 s80, s42, s30
	s_addc_u32 s81, s43, 0
	s_add_u32 s86, s80, 0x7c000
	s_addc_u32 s87, s81, 0
	s_add_u32 s96, s46, s30
	s_addc_u32 s97, s47, 0
	s_add_u32 s98, s96, 0x7c000
	s_addc_u32 s99, s97, 0
	global_load_dwordx4 v[212:215], v173, s[80:81]
	global_load_dwordx4 v[220:223], v175, s[96:97]
	global_load_dwordx4 v[216:219], v173, s[86:87]
	global_load_dwordx4 v[224:227], v175, s[98:99]
	ds_read_b128 v[228:231], v255 offset:18432
	ds_read_b128 v[232:235], v255 offset:18496
	ds_read_b128 v[236:239], v255 offset:23040
	ds_read_b128 v[240:243], v255 offset:23104
	v_max3_f32 v26, v88, v89, v90
	v_max3_f32 v26, v26, v91, v92
	v_max3_f32 v26, v26, v93, v94
	v_max3_f32 v26, v26, v95, v96
	v_max3_f32 v26, v26, v97, v98
	v_max3_f32 v26, v26, v99, v100
	v_max3_f32 v26, v26, v101, v102
	v_max_f32_e32 v26, v26, v103
	v_cmp_lt_f32_e32 vcc, s66, v26
	s_cbranch_vccz .Ld_nr_B1_0
	v_mov_b32_e32 v27, v26
	s_nop 1
	v_permlane16_swap_b32_e32 v26, v27
	v_max_f32_e32 v26, v26, v27
	v_mov_b32_e32 v27, v26
	s_nop 1
	v_permlane32_swap_b32_e32 v26, v27
	v_max_f32_e32 v26, v26, v27
	v_cmp_lt_f32_e32 vcc, s66, v26
	s_nop 1
	v_cndmask_b32_e32 v3, 0, v26, vcc
	v_sub_f32_e32 v2, 0, v3
	v_min_f32_e32 v2, 0, v2
	v_exp_f32_e32 v2, v2
	v_sub_f32_e32 v24, v24, v3
	v_mul_f32_e32 v0, v0, v2
	v_mul_f32_e32 v28, v28, v2
	v_mul_f32_e32 v29, v29, v2
	v_mul_f32_e32 v30, v30, v2
	v_mul_f32_e32 v31, v31, v2
	v_mul_f32_e32 v32, v32, v2
	v_mul_f32_e32 v33, v33, v2
	v_mul_f32_e32 v34, v34, v2
	v_mul_f32_e32 v35, v35, v2
	v_mul_f32_e32 v40, v40, v2
	v_mul_f32_e32 v41, v41, v2
	v_mul_f32_e32 v42, v42, v2
	v_mul_f32_e32 v43, v43, v2
	v_mul_f32_e32 v52, v52, v2
	v_mul_f32_e32 v53, v53, v2
	v_mul_f32_e32 v54, v54, v2
	v_mul_f32_e32 v55, v55, v2
	v_mul_f32_e32 v56, v56, v2
	v_mul_f32_e32 v57, v57, v2
	v_mul_f32_e32 v58, v58, v2
	v_mul_f32_e32 v59, v59, v2
	v_mul_f32_e32 v64, v64, v2
	v_mul_f32_e32 v65, v65, v2
	v_mul_f32_e32 v66, v66, v2
	v_mul_f32_e32 v67, v67, v2
	v_mul_f32_e32 v72, v72, v2
	v_mul_f32_e32 v73, v73, v2
	v_mul_f32_e32 v74, v74, v2
	v_mul_f32_e32 v75, v75, v2
	v_mul_f32_e32 v84, v84, v2
	v_mul_f32_e32 v85, v85, v2
	v_mul_f32_e32 v86, v86, v2
	v_mul_f32_e32 v87, v87, v2
	v_sub_f32_e32 v88, v88, v3
	v_sub_f32_e32 v89, v89, v3
	v_sub_f32_e32 v90, v90, v3
	v_sub_f32_e32 v91, v91, v3
	v_sub_f32_e32 v92, v92, v3
	v_sub_f32_e32 v93, v93, v3
	v_sub_f32_e32 v94, v94, v3
	v_sub_f32_e32 v95, v95, v3
	v_sub_f32_e32 v96, v96, v3
	v_sub_f32_e32 v97, v97, v3
	v_sub_f32_e32 v98, v98, v3
	v_sub_f32_e32 v99, v99, v3
	v_sub_f32_e32 v100, v100, v3
	v_sub_f32_e32 v101, v101, v3
	v_sub_f32_e32 v102, v102, v3
	v_sub_f32_e32 v103, v103, v3

.Ld_nr_B1_1:
	v_exp_f32_e32 v104, v104
	v_exp_f32_e32 v105, v105
	v_exp_f32_e32 v106, v106
	v_exp_f32_e32 v107, v107
	v_exp_f32_e32 v108, v108
	v_exp_f32_e32 v109, v109
	v_exp_f32_e32 v110, v110
	v_exp_f32_e32 v111, v111
	v_exp_f32_e32 v112, v112
	v_exp_f32_e32 v113, v113
	v_exp_f32_e32 v114, v114
	v_exp_f32_e32 v115, v115
	v_exp_f32_e32 v116, v116
	v_exp_f32_e32 v117, v117
	v_exp_f32_e32 v118, v118
	v_exp_f32_e32 v119, v119
	s_nop 0
	v_add_f32_e32 v26, v104, v105
	v_add_f32_e32 v26, v26, v106
	v_add_f32_e32 v26, v26, v107
	v_add_f32_e32 v26, v26, v108
	v_add_f32_e32 v26, v26, v109
	v_add_f32_e32 v26, v26, v110
	v_add_f32_e32 v26, v26, v111
	v_add_f32_e32 v26, v26, v112
	v_add_f32_e32 v26, v26, v113
	v_add_f32_e32 v26, v26, v114
	v_add_f32_e32 v26, v26, v115
	v_add_f32_e32 v26, v26, v116
	v_add_f32_e32 v26, v26, v117
	v_add_f32_e32 v26, v26, v118
	v_add_f32_e32 v26, v26, v119
	v_add_f32_e32 v151, v151, v26
	v_cvt_pk_bf16_f32 v128, v104, v105
	v_cvt_pk_bf16_f32 v129, v106, v107
	v_cvt_pk_bf16_f32 v130, v108, v109
	v_cvt_pk_bf16_f32 v131, v110, v111
	v_cvt_pk_bf16_f32 v152, v112, v113
	v_cvt_pk_bf16_f32 v153, v114, v115
	v_cvt_pk_bf16_f32 v154, v116, v117
	v_cvt_pk_bf16_f32 v155, v118, v119
	v_mov_b32_e32 v156, v165
	v_add_f32_e32 v157, 0x3f800000, v165
	v_add_f32_e32 v158, 0x40000000, v165
	v_add_f32_e32 v159, 0x40400000, v165
	v_add_f32_e32 v160, 0x41800000, v165
	v_add_f32_e32 v161, 0x41880000, v165
	v_add_f32_e32 v162, 0x41900000, v165
	v_add_f32_e32 v163, 0x41980000, v165
	v_add_f32_e32 v176, 0x42000000, v165
	v_add_f32_e32 v177, 0x42040000, v165
	v_add_f32_e32 v178, 0x42080000, v165
	v_add_f32_e32 v179, 0x420c0000, v165
	v_add_f32_e32 v180, 0x42400000, v165
	v_add_f32_e32 v181, 0x42440000, v165
	v_add_f32_e32 v182, 0x42480000, v165
	v_add_f32_e32 v183, 0x424c0000, v165
	v_fma_f32 v204, -v150, |v156|, v25
	v_fma_f32 v205, -v150, |v157|, v25
	v_fma_f32 v206, -v150, |v158|, v25
	v_fma_f32 v207, -v150, |v159|, v25
	v_fma_f32 v208, -v150, |v160|, v25
	v_fma_f32 v209, -v150, |v161|, v25
	v_fma_f32 v210, -v150, |v162|, v25
	v_fma_f32 v211, -v150, |v163|, v25
	v_fma_f32 v184, -v150, |v176|, v25
	v_fma_f32 v185, -v150, |v177|, v25
	v_fma_f32 v186, -v150, |v178|, v25
	v_fma_f32 v187, -v150, |v179|, v25
	v_fma_f32 v188, -v150, |v180|, v25
	v_fma_f32 v189, -v150, |v181|, v25
	v_fma_f32 v190, -v150, |v182|, v25
	v_fma_f32 v191, -v150, |v183|, v25
	v_fma_f32 v156, -v150, |v156|, v24
	v_fma_f32 v157, -v150, |v157|, v24
	v_fma_f32 v158, -v150, |v158|, v24
	v_fma_f32 v159, -v150, |v159|, v24
	v_fma_f32 v160, -v150, |v160|, v24
	v_fma_f32 v161, -v150, |v161|, v24
	v_fma_f32 v162, -v150, |v162|, v24
	v_fma_f32 v163, -v150, |v163|, v24
	v_fma_f32 v176, -v150, |v176|, v24
	v_fma_f32 v177, -v150, |v177|, v24
	v_fma_f32 v178, -v150, |v178|, v24
	v_fma_f32 v179, -v150, |v179|, v24
	v_fma_f32 v180, -v150, |v180|, v24
	v_fma_f32 v181, -v150, |v181|, v24
	v_fma_f32 v182, -v150, |v182|, v24
	v_fma_f32 v183, -v150, |v183|, v24
	ds_read_b128 v[244:247], v255 offset:27648
	s_waitcnt lgkmcnt(4)
	v_mfma_f32_16x16x32_bf16 v[88:91], v[228:231], v[4:7], v[156:159]
	ds_read_b128 v[248:251], v255 offset:27712
	s_waitcnt lgkmcnt(4)
	v_mfma_f32_16x16x32_bf16 v[88:91], v[232:235], v[8:11], v[88:91]
	ds_read_b128 v[228:231], v255 offset:32256
	s_waitcnt lgkmcnt(4)
	v_mfma_f32_16x16x32_bf16 v[92:95], v[236:239], v[4:7], v[160:163]
	ds_read_b128 v[232:235], v255 offset:32320
	s_waitcnt lgkmcnt(4)
	v_mfma_f32_16x16x32_bf16 v[92:95], v[240:243], v[8:11], v[92:95]
	ds_read_b128 v[236:239], v255 offset:18560
	s_waitcnt lgkmcnt(4)
	v_mfma_f32_16x16x32_bf16 v[96:99], v[244:247], v[4:7], v[176:179]
	ds_read_b128 v[240:243], v255 offset:18624
	s_waitcnt lgkmcnt(4)
	v_mfma_f32_16x16x32_bf16 v[96:99], v[248:251], v[8:11], v[96:99]
	ds_read_b128 v[244:247], v255 offset:23168
	s_waitcnt lgkmcnt(4)
	v_mfma_f32_16x16x32_bf16 v[100:103], v[228:231], v[4:7], v[180:183]
	ds_read_b128 v[248:251], v255 offset:23232
	s_waitcnt lgkmcnt(4)
	v_mfma_f32_16x16x32_bf16 v[100:103], v[232:235], v[8:11], v[100:103]
	ds_read_b128 v[228:231], v255 offset:27776
	s_waitcnt lgkmcnt(4)
	v_mfma_f32_16x16x32_bf16 v[104:107], v[236:239], v[12:15], v[204:207]
	ds_read_b128 v[232:235], v255 offset:27840
	s_waitcnt lgkmcnt(4)
	v_mfma_f32_16x16x32_bf16 v[104:107], v[240:243], v[16:19], v[104:107]
	ds_read_b128 v[236:239], v255 offset:32384
	s_waitcnt lgkmcnt(4)
	v_mfma_f32_16x16x32_bf16 v[108:111], v[244:247], v[12:15], v[208:211]
	ds_read_b128 v[240:243], v255 offset:32448
	s_waitcnt lgkmcnt(4)
	v_mfma_f32_16x16x32_bf16 v[108:111], v[248:251], v[16:19], v[108:111]
	ds_read_b64_tr_b16 v[244:245], v174 offset:36864
	ds_read_b64_tr_b16 v[246:247], v174 offset:41472
	s_waitcnt lgkmcnt(5)
	v_mfma_f32_16x16x32_bf16 v[112:115], v[228:231], v[12:15], v[184:187]
	ds_read_b64_tr_b16 v[248:249], v174 offset:36896
	ds_read_b64_tr_b16 v[250:251], v174 offset:41504
	s_waitcnt lgkmcnt(6)
	v_mfma_f32_16x16x32_bf16 v[112:115], v[232:235], v[16:19], v[112:115]
	ds_read_b64_tr_b16 v[228:229], v174 offset:36928
	ds_read_b64_tr_b16 v[230:231], v174 offset:41536
	s_waitcnt lgkmcnt(7)
	v_mfma_f32_16x16x32_bf16 v[116:119], v[236:239], v[12:15], v[188:191]
	ds_read_b64_tr_b16 v[232:233], v174 offset:36960
	ds_read_b64_tr_b16 v[234:235], v174 offset:41568
	s_waitcnt lgkmcnt(8)
	v_mfma_f32_16x16x32_bf16 v[116:119], v[240:243], v[16:19], v[116:119]
	ds_read_b64_tr_b16 v[236:237], v174 offset:36992
	ds_read_b64_tr_b16 v[238:239], v174 offset:41600
	s_waitcnt lgkmcnt(8)
	v_mfma_f32_16x16x32_bf16 v[28:31], v[244:247], v[120:123], v[28:31]
	v_mfma_f32_16x16x32_bf16 v[36:39], v[244:247], v[128:131], v[36:39]
	ds_read_b64_tr_b16 v[240:241], v174 offset:37024
	ds_read_b64_tr_b16 v[242:243], v174 offset:41632
	s_waitcnt lgkmcnt(8)
	v_mfma_f32_16x16x32_bf16 v[32:35], v[248:251], v[120:123], v[32:35]
	v_mfma_f32_16x16x32_bf16 v[44:47], v[248:251], v[128:131], v[44:47]
	ds_read_b64_tr_b16 v[244:245], v174 offset:37056
	ds_read_b64_tr_b16 v[246:247], v174 offset:41664
	s_waitcnt lgkmcnt(8)
	v_mfma_f32_16x16x32_bf16 v[40:43], v[228:231], v[120:123], v[40:43]
	v_mfma_f32_16x16x32_bf16 v[48:51], v[228:231], v[128:131], v[48:51]
	ds_read_b64_tr_b16 v[248:249], v174 offset:37088
	ds_read_b64_tr_b16 v[250:251], v174 offset:41696
	s_waitcnt lgkmcnt(8)
	v_mfma_f32_16x16x32_bf16 v[52:55], v[232:235], v[120:123], v[52:55]
	v_mfma_f32_16x16x32_bf16 v[60:63], v[232:235], v[128:131], v[60:63]
	ds_read_b64_tr_b16 v[228:229], v174 offset:46080
	ds_read_b64_tr_b16 v[230:231], v174 offset:50688
	s_waitcnt lgkmcnt(8)
	v_mfma_f32_16x16x32_bf16 v[56:59], v[236:239], v[120:123], v[56:59]
	v_mfma_f32_16x16x32_bf16 v[68:71], v[236:239], v[128:131], v[68:71]
	ds_read_b64_tr_b16 v[232:233], v174 offset:46112
	ds_read_b64_tr_b16 v[234:235], v174 offset:50720
	s_waitcnt lgkmcnt(8)
	v_mfma_f32_16x16x32_bf16 v[64:67], v[240:243], v[120:123], v[64:67]
	v_mfma_f32_16x16x32_bf16 v[76:79], v[240:243], v[128:131], v[76:79]
	ds_read_b64_tr_b16 v[236:237], v174 offset:46144
	ds_read_b64_tr_b16 v[238:239], v174 offset:50752
	s_waitcnt lgkmcnt(8)
	v_mfma_f32_16x16x32_bf16 v[72:75], v[244:247], v[120:123], v[72:75]
	v_mfma_f32_16x16x32_bf16 v[80:83], v[244:247], v[128:131], v[80:83]
	ds_read_b64_tr_b16 v[240:241], v174 offset:46176
	ds_read_b64_tr_b16 v[242:243], v174 offset:50784
	s_waitcnt lgkmcnt(8)
	v_mfma_f32_16x16x32_bf16 v[84:87], v[248:251], v[120:123], v[84:87]
	v_mfma_f32_16x16x32_bf16 v[20:23], v[248:251], v[128:131], v[20:23]
	ds_read_b64_tr_b16 v[244:245], v174 offset:46208
	ds_read_b64_tr_b16 v[246:247], v174 offset:50816
	s_waitcnt lgkmcnt(8)
	v_mfma_f32_16x16x32_bf16 v[28:31], v[228:231], v[124:127], v[28:31]
	v_mfma_f32_16x16x32_bf16 v[36:39], v[228:231], v[152:155], v[36:39]
	ds_read_b64_tr_b16 v[248:249], v174 offset:46240
	ds_read_b64_tr_b16 v[250:251], v174 offset:50848
	s_waitcnt lgkmcnt(8)
	v_mfma_f32_16x16x32_bf16 v[32:35], v[232:235], v[124:127], v[32:35]
	v_mfma_f32_16x16x32_bf16 v[44:47], v[232:235], v[152:155], v[44:47]
	ds_read_b64_tr_b16 v[228:229], v174 offset:46272
	ds_read_b64_tr_b16 v[230:231], v174 offset:50880
	s_waitcnt lgkmcnt(8)
	v_mfma_f32_16x16x32_bf16 v[40:43], v[236:239], v[124:127], v[40:43]
	v_mfma_f32_16x16x32_bf16 v[48:51], v[236:239], v[152:155], v[48:51]
	ds_read_b64_tr_b16 v[232:233], v174 offset:46304
	ds_read_b64_tr_b16 v[234:235], v174 offset:50912
	s_waitcnt lgkmcnt(8)
	v_mfma_f32_16x16x32_bf16 v[52:55], v[240:243], v[124:127], v[52:55]
	v_mfma_f32_16x16x32_bf16 v[60:63], v[240:243], v[152:155], v[60:63]
	s_waitcnt lgkmcnt(6)
	v_mfma_f32_16x16x32_bf16 v[56:59], v[244:247], v[124:127], v[56:59]
	v_mfma_f32_16x16x32_bf16 v[68:71], v[244:247], v[152:155], v[68:71]
	s_waitcnt lgkmcnt(4)
	v_mfma_f32_16x16x32_bf16 v[64:67], v[248:251], v[124:127], v[64:67]
	v_mfma_f32_16x16x32_bf16 v[76:79], v[248:251], v[152:155], v[76:79]
	s_waitcnt lgkmcnt(2)
	v_mfma_f32_16x16x32_bf16 v[72:75], v[228:231], v[124:127], v[72:75]
	v_mfma_f32_16x16x32_bf16 v[80:83], v[228:231], v[152:155], v[80:83]
	s_waitcnt lgkmcnt(0)
	v_mfma_f32_16x16x32_bf16 v[84:87], v[232:235], v[124:127], v[84:87]
	v_mfma_f32_16x16x32_bf16 v[20:23], v[232:235], v[152:155], v[20:23]
	s_waitcnt vmcnt(0)
	ds_write_b128 v169, v[212:215] offset:0
	ds_write_b128 v169, v[216:219] offset:9216
	ds_write_b128 v164, v[220:223] offset:36864
	ds_write_b128 v164, v[224:227] offset:46080
	s_mov_b32 s31, s38
	s_mov_b32 s38, s39
	s_add_i32 s39, s39, 0x4800
	s_cmp_lg_u32 s39, 0xd800
	s_cselect_b32 s39, s39, 0
	s_mov_b32 s66, 0xff800000
	s_cmp_ge_u32 s5, 1
	s_cselect_b32 s66, 0x42800000, s66
	s_add_i32 s5, s5, 1
	s_min_u32 s8, s5, 62
	s_add_i32 s8, s8, 1
	s_mul_i32 s30, s8, 0xf8000
	v_add_f32_e32 v165, 0x42800000, v165
	s_waitcnt lgkmcnt(0)
	s_barrier
	s_cmp_lt_u32 s5, 64
	s_cbranch_scc1 .Ld_loopB
	v_add_u32_e32 v174, s31, v168
	ds_read_b64_tr_b16 v[228:229], v174 offset:36864
	ds_read_b64_tr_b16 v[230:231], v174 offset:41472
	ds_read_b64_tr_b16 v[232:233], v174 offset:36896
	ds_read_b64_tr_b16 v[234:235], v174 offset:41504
	ds_read_b64_tr_b16 v[236:237], v174 offset:36928
	ds_read_b64_tr_b16 v[238:239], v174 offset:41536
	ds_read_b64_tr_b16 v[240:241], v174 offset:36960
	ds_read_b64_tr_b16 v[242:243], v174 offset:41568
	v_max3_f32 v26, v88, v89, v90
	v_max3_f32 v26, v26, v91, v92
	v_max3_f32 v26, v26, v93, v94
	v_max3_f32 v26, v26, v95, v96
	v_max3_f32 v26, v26, v97, v98
	v_max3_f32 v26, v26, v99, v100
	v_max3_f32 v26, v26, v101, v102
	v_max_f32_e32 v26, v26, v103
	v_cmp_lt_f32_e32 vcc, s66, v26
	s_cbranch_vccz .Ld_nr_Bt_0
	v_mov_b32_e32 v27, v26
	s_nop 1
	v_permlane16_swap_b32_e32 v26, v27
	v_max_f32_e32 v26, v26, v27
	v_mov_b32_e32 v27, v26
	s_nop 1
	v_permlane32_swap_b32_e32 v26, v27
	v_max_f32_e32 v26, v26, v27
	v_cmp_lt_f32_e32 vcc, s66, v26
	s_nop 1
	v_cndmask_b32_e32 v3, 0, v26, vcc
	v_sub_f32_e32 v2, 0, v3
	v_min_f32_e32 v2, 0, v2
	v_exp_f32_e32 v2, v2
	v_sub_f32_e32 v24, v24, v3
	v_mul_f32_e32 v0, v0, v2
	v_mul_f32_e32 v28, v28, v2
	v_mul_f32_e32 v29, v29, v2
	v_mul_f32_e32 v30, v30, v2
	v_mul_f32_e32 v31, v31, v2
	v_mul_f32_e32 v32, v32, v2
	v_mul_f32_e32 v33, v33, v2
	v_mul_f32_e32 v34, v34, v2
	v_mul_f32_e32 v35, v35, v2
	v_mul_f32_e32 v40, v40, v2
	v_mul_f32_e32 v41, v41, v2
	v_mul_f32_e32 v42, v42, v2
	v_mul_f32_e32 v43, v43, v2
	v_mul_f32_e32 v52, v52, v2
	v_mul_f32_e32 v53, v53, v2
	v_mul_f32_e32 v54, v54, v2
	v_mul_f32_e32 v55, v55, v2
	v_mul_f32_e32 v56, v56, v2
	v_mul_f32_e32 v57, v57, v2
	v_mul_f32_e32 v58, v58, v2
	v_mul_f32_e32 v59, v59, v2
	v_mul_f32_e32 v64, v64, v2
	v_mul_f32_e32 v65, v65, v2
	v_mul_f32_e32 v66, v66, v2
	v_mul_f32_e32 v67, v67, v2
	v_mul_f32_e32 v72, v72, v2
	v_mul_f32_e32 v73, v73, v2
	v_mul_f32_e32 v74, v74, v2
	v_mul_f32_e32 v75, v75, v2
	v_mul_f32_e32 v84, v84, v2
	v_mul_f32_e32 v85, v85, v2
	v_mul_f32_e32 v86, v86, v2
	v_mul_f32_e32 v87, v87, v2
	v_sub_f32_e32 v88, v88, v3
	v_sub_f32_e32 v89, v89, v3
	v_sub_f32_e32 v90, v90, v3
	v_sub_f32_e32 v91, v91, v3
	v_sub_f32_e32 v92, v92, v3
	v_sub_f32_e32 v93, v93, v3
	v_sub_f32_e32 v94, v94, v3
	v_sub_f32_e32 v95, v95, v3
	v_sub_f32_e32 v96, v96, v3
	v_sub_f32_e32 v97, v97, v3
	v_sub_f32_e32 v98, v98, v3
	v_sub_f32_e32 v99, v99, v3
	v_sub_f32_e32 v100, v100, v3
	v_sub_f32_e32 v101, v101, v3
	v_sub_f32_e32 v102, v102, v3
	v_sub_f32_e32 v103, v103, v3

.Ld_groupA:
	v_mov_b32_e32 v28, 0
	v_mov_b32_e32 v29, 0
	v_mov_b32_e32 v30, 0
	v_mov_b32_e32 v31, 0
	v_mov_b32_e32 v32, 0
	v_mov_b32_e32 v33, 0
	v_mov_b32_e32 v34, 0
	v_mov_b32_e32 v35, 0
	v_mov_b32_e32 v40, 0
	v_mov_b32_e32 v41, 0
	v_mov_b32_e32 v42, 0
	v_mov_b32_e32 v43, 0
	v_mov_b32_e32 v52, 0
	v_mov_b32_e32 v53, 0
	v_mov_b32_e32 v54, 0
	v_mov_b32_e32 v55, 0
	v_mov_b32_e32 v56, 0
	v_mov_b32_e32 v57, 0
	v_mov_b32_e32 v58, 0
	v_mov_b32_e32 v59, 0
	v_mov_b32_e32 v64, 0
	v_mov_b32_e32 v65, 0
	v_mov_b32_e32 v66, 0
	v_mov_b32_e32 v67, 0
	v_mov_b32_e32 v72, 0
	v_mov_b32_e32 v73, 0
	v_mov_b32_e32 v74, 0
	v_mov_b32_e32 v75, 0
	v_mov_b32_e32 v84, 0
	v_mov_b32_e32 v85, 0
	v_mov_b32_e32 v86, 0
	v_mov_b32_e32 v87, 0
	v_mov_b32_e32 v36, 0
	v_mov_b32_e32 v37, 0
	v_mov_b32_e32 v38, 0
	v_mov_b32_e32 v39, 0
	v_mov_b32_e32 v44, 0
	v_mov_b32_e32 v45, 0
	v_mov_b32_e32 v46, 0
	v_mov_b32_e32 v47, 0
	v_mov_b32_e32 v48, 0
	v_mov_b32_e32 v49, 0
	v_mov_b32_e32 v50, 0
	v_mov_b32_e32 v51, 0
	v_mov_b32_e32 v60, 0
	v_mov_b32_e32 v61, 0
	v_mov_b32_e32 v62, 0
	v_mov_b32_e32 v63, 0
	v_mov_b32_e32 v68, 0
	v_mov_b32_e32 v69, 0
	v_mov_b32_e32 v70, 0
	v_mov_b32_e32 v71, 0
	v_mov_b32_e32 v76, 0
	v_mov_b32_e32 v77, 0
	v_mov_b32_e32 v78, 0
	v_mov_b32_e32 v79, 0
	v_mov_b32_e32 v80, 0
	v_mov_b32_e32 v81, 0
	v_mov_b32_e32 v82, 0
	v_mov_b32_e32 v83, 0
	v_mov_b32_e32 v20, 0
	v_mov_b32_e32 v21, 0
	v_mov_b32_e32 v22, 0
	v_mov_b32_e32 v23, 0
	v_mov_b32_e32 v120, 0
	v_mov_b32_e32 v121, 0
	v_mov_b32_e32 v122, 0
	v_mov_b32_e32 v123, 0
	v_mov_b32_e32 v124, 0
	v_mov_b32_e32 v125, 0
	v_mov_b32_e32 v126, 0
	v_mov_b32_e32 v127, 0
	v_mov_b32_e32 v128, 0
	v_mov_b32_e32 v129, 0
	v_mov_b32_e32 v130, 0
	v_mov_b32_e32 v131, 0
	v_mov_b32_e32 v152, 0
	v_mov_b32_e32 v153, 0
	v_mov_b32_e32 v154, 0
	v_mov_b32_e32 v155, 0
	v_mov_b32_e32 v0, 0
	v_mov_b32_e32 v151, 0
	v_mov_b32_e32 v24, 0
	v_mov_b32_e32 v25, 0
	s_mov_b32 s66, 0xff800000
	v_add_u32_e32 v255, v171, v172
	v_mov_b32_e32 v165, v170
	v_readfirstlane_b32 s42, v134
	v_readfirstlane_b32 s43, v135
	v_readfirstlane_b32 s46, v136
	v_readfirstlane_b32 s47, v137
	s_nop 3
	v_subrev_u32_e32 v173, s42, v134
	v_subrev_u32_e32 v175, s46, v136
	s_mov_b32 s5, 0
	s_mov_b32 s31, 0
	s_mov_b32 s38, 0
	s_mov_b32 s39, 0x4800
	s_mov_b32 s30, 0xf8000
	v_mov_b32_e32 v156, v165
	v_add_f32_e32 v157, 0x3f800000, v165
	v_add_f32_e32 v158, 0x40000000, v165
	v_add_f32_e32 v159, 0x40400000, v165
	v_add_f32_e32 v160, 0x41800000, v165
	v_add_f32_e32 v161, 0x41880000, v165
	v_add_f32_e32 v162, 0x41900000, v165
	v_add_f32_e32 v163, 0x41980000, v165
	v_add_f32_e32 v176, 0x42000000, v165
	v_add_f32_e32 v177, 0x42040000, v165
	v_add_f32_e32 v178, 0x42080000, v165
	v_add_f32_e32 v179, 0x420c0000, v165
	v_add_f32_e32 v180, 0x42400000, v165
	v_add_f32_e32 v181, 0x42440000, v165
	v_add_f32_e32 v182, 0x42480000, v165
	v_add_f32_e32 v183, 0x424c0000, v165
	v_fma_f32 v204, -v150, |v156|, v25
	v_fma_f32 v205, -v150, |v157|, v25
	v_fma_f32 v206, -v150, |v158|, v25
	v_fma_f32 v207, -v150, |v159|, v25
	v_fma_f32 v208, -v150, |v160|, v25
	v_fma_f32 v209, -v150, |v161|, v25
	v_fma_f32 v210, -v150, |v162|, v25
	v_fma_f32 v211, -v150, |v163|, v25
	v_fma_f32 v184, -v150, |v176|, v25
	v_fma_f32 v185, -v150, |v177|, v25
	v_fma_f32 v186, -v150, |v178|, v25
	v_fma_f32 v187, -v150, |v179|, v25
	v_fma_f32 v188, -v150, |v180|, v25
	v_fma_f32 v189, -v150, |v181|, v25
	v_fma_f32 v190, -v150, |v182|, v25
	v_fma_f32 v191, -v150, |v183|, v25
	v_fma_f32 v156, -v150, |v156|, v24
	v_fma_f32 v157, -v150, |v157|, v24
	v_fma_f32 v158, -v150, |v158|, v24
	v_fma_f32 v159, -v150, |v159|, v24
	v_fma_f32 v160, -v150, |v160|, v24
	v_fma_f32 v161, -v150, |v161|, v24
	v_fma_f32 v162, -v150, |v162|, v24
	v_fma_f32 v163, -v150, |v163|, v24
	v_fma_f32 v176, -v150, |v176|, v24
	v_fma_f32 v177, -v150, |v177|, v24
	v_fma_f32 v178, -v150, |v178|, v24
	v_fma_f32 v179, -v150, |v179|, v24
	v_fma_f32 v180, -v150, |v180|, v24
	v_fma_f32 v181, -v150, |v181|, v24
	v_fma_f32 v182, -v150, |v182|, v24
	v_fma_f32 v183, -v150, |v183|, v24
.Ld_loopA:
	v_add_u32_e32 v174, s31, v168
	v_add_u32_e32 v164, s39, v169
	s_add_u32 s80, s42, s30
	s_addc_u32 s81, s43, 0
	s_add_u32 s86, s80, 0x7c000
	s_addc_u32 s87, s81, 0
	s_add_u32 s96, s46, s30
	s_addc_u32 s97, s47, 0
	s_add_u32 s98, s96, 0x7c000
	s_addc_u32 s99, s97, 0
	global_load_dwordx4 v[212:215], v173, s[80:81]
	global_load_dwordx4 v[220:223], v175, s[96:97]
	global_load_dwordx4 v[216:219], v173, s[86:87]
	global_load_dwordx4 v[224:227], v175, s[98:99]
	ds_read_b64_tr_b16 v[228:229], v174 offset:36864
	ds_read_b64_tr_b16 v[230:231], v174 offset:41472
	ds_read_b64_tr_b16 v[232:233], v174 offset:36896
	ds_read_b64_tr_b16 v[234:235], v174 offset:41504
	ds_read_b64_tr_b16 v[236:237], v174 offset:36928
	ds_read_b64_tr_b16 v[238:239], v174 offset:41536
	ds_read_b64_tr_b16 v[240:241], v174 offset:36960
	ds_read_b64_tr_b16 v[242:243], v174 offset:41568
	ds_read_b64_tr_b16 v[244:245], v174 offset:36992
	ds_read_b64_tr_b16 v[246:247], v174 offset:41600
	s_waitcnt lgkmcnt(8)
	v_mfma_f32_16x16x32_bf16 v[28:31], v[228:231], v[120:123], v[28:31]
	v_mfma_f32_16x16x32_bf16 v[36:39], v[228:231], v[128:131], v[36:39]
	ds_read_b64_tr_b16 v[248:249], v174 offset:37024
	ds_read_b64_tr_b16 v[250:251], v174 offset:41632
	s_waitcnt lgkmcnt(8)
	v_mfma_f32_16x16x32_bf16 v[32:35], v[232:235], v[120:123], v[32:35]
	v_mfma_f32_16x16x32_bf16 v[44:47], v[232:235], v[128:131], v[44:47]
	ds_read_b64_tr_b16 v[228:229], v174 offset:37056
	ds_read_b64_tr_b16 v[230:231], v174 offset:41664
	s_waitcnt lgkmcnt(8)
	v_mfma_f32_16x16x32_bf16 v[40:43], v[236:239], v[120:123], v[40:43]
	v_mfma_f32_16x16x32_bf16 v[48:51], v[236:239], v[128:131], v[48:51]
	ds_read_b64_tr_b16 v[232:233], v174 offset:37088
	ds_read_b64_tr_b16 v[234:235], v174 offset:41696
	s_waitcnt lgkmcnt(8)
	v_mfma_f32_16x16x32_bf16 v[52:55], v[240:243], v[120:123], v[52:55]
	v_mfma_f32_16x16x32_bf16 v[60:63], v[240:243], v[128:131], v[60:63]
	ds_read_b64_tr_b16 v[236:237], v174 offset:46080
	ds_read_b64_tr_b16 v[238:239], v174 offset:50688
	s_waitcnt lgkmcnt(8)
	v_mfma_f32_16x16x32_bf16 v[56:59], v[244:247], v[120:123], v[56:59]
	v_mfma_f32_16x16x32_bf16 v[68:71], v[244:247], v[128:131], v[68:71]
	ds_read_b64_tr_b16 v[240:241], v174 offset:46112
	ds_read_b64_tr_b16 v[242:243], v174 offset:50720
	s_waitcnt lgkmcnt(8)
	v_mfma_f32_16x16x32_bf16 v[64:67], v[248:251], v[120:123], v[64:67]
	v_mfma_f32_16x16x32_bf16 v[76:79], v[248:251], v[128:131], v[76:79]
	ds_read_b64_tr_b16 v[244:245], v174 offset:46144
	ds_read_b64_tr_b16 v[246:247], v174 offset:50752
	s_waitcnt lgkmcnt(8)
	v_mfma_f32_16x16x32_bf16 v[72:75], v[228:231], v[120:123], v[72:75]
	v_mfma_f32_16x16x32_bf16 v[80:83], v[228:231], v[128:131], v[80:83]
	ds_read_b64_tr_b16 v[248:249], v174 offset:46176
	ds_read_b64_tr_b16 v[250:251], v174 offset:50784
	s_waitcnt lgkmcnt(8)
	v_mfma_f32_16x16x32_bf16 v[84:87], v[232:235], v[120:123], v[84:87]
	v_mfma_f32_16x16x32_bf16 v[20:23], v[232:235], v[128:131], v[20:23]
	ds_read_b64_tr_b16 v[228:229], v174 offset:46208
	ds_read_b64_tr_b16 v[230:231], v174 offset:50816
	s_waitcnt lgkmcnt(8)
	v_mfma_f32_16x16x32_bf16 v[28:31], v[236:239], v[124:127], v[28:31]
	v_mfma_f32_16x16x32_bf16 v[36:39], v[236:239], v[152:155], v[36:39]
	ds_read_b64_tr_b16 v[232:233], v174 offset:46240
	ds_read_b64_tr_b16 v[234:235], v174 offset:50848
	s_waitcnt lgkmcnt(8)
	v_mfma_f32_16x16x32_bf16 v[32:35], v[240:243], v[124:127], v[32:35]
	v_mfma_f32_16x16x32_bf16 v[44:47], v[240:243], v[152:155], v[44:47]
	ds_read_b64_tr_b16 v[236:237], v174 offset:46272
	ds_read_b64_tr_b16 v[238:239], v174 offset:50880
	s_waitcnt lgkmcnt(8)
	v_mfma_f32_16x16x32_bf16 v[40:43], v[244:247], v[124:127], v[40:43]
	v_mfma_f32_16x16x32_bf16 v[48:51], v[244:247], v[152:155], v[48:51]
	ds_read_b64_tr_b16 v[240:241], v174 offset:46304
	ds_read_b64_tr_b16 v[242:243], v174 offset:50912
	s_waitcnt lgkmcnt(8)
	v_mfma_f32_16x16x32_bf16 v[52:55], v[248:251], v[124:127], v[52:55]
	v_mfma_f32_16x16x32_bf16 v[60:63], v[248:251], v[152:155], v[60:63]
	ds_read_b128 v[244:247], v255 offset:0
	s_waitcnt lgkmcnt(7)
	v_mfma_f32_16x16x32_bf16 v[56:59], v[228:231], v[124:127], v[56:59]
	v_mfma_f32_16x16x32_bf16 v[68:71], v[228:231], v[152:155], v[68:71]
	ds_read_b128 v[248:251], v255 offset:64
	s_waitcnt lgkmcnt(6)
	v_mfma_f32_16x16x32_bf16 v[64:67], v[232:235], v[124:127], v[64:67]
	v_mfma_f32_16x16x32_bf16 v[76:79], v[232:235], v[152:155], v[76:79]
	ds_read_b128 v[228:231], v255 offset:4608
	s_waitcnt lgkmcnt(5)
	v_mfma_f32_16x16x32_bf16 v[72:75], v[236:239], v[124:127], v[72:75]
	v_mfma_f32_16x16x32_bf16 v[80:83], v[236:239], v[152:155], v[80:83]
	ds_read_b128 v[232:235], v255 offset:4672
	s_waitcnt lgkmcnt(4)
	v_mfma_f32_16x16x32_bf16 v[84:87], v[240:243], v[124:127], v[84:87]
	v_mfma_f32_16x16x32_bf16 v[20:23], v[240:243], v[152:155], v[20:23]
	ds_read_b128 v[236:239], v255 offset:9216
	s_waitcnt lgkmcnt(4)
	v_mfma_f32_16x16x32_bf16 v[88:91], v[244:247], v[4:7], v[156:159]
	ds_read_b128 v[240:243], v255 offset:9280
	s_waitcnt lgkmcnt(4)
	v_mfma_f32_16x16x32_bf16 v[88:91], v[248:251], v[8:11], v[88:91]
	ds_read_b128 v[244:247], v255 offset:13824
	s_waitcnt lgkmcnt(4)
	v_mfma_f32_16x16x32_bf16 v[92:95], v[228:231], v[4:7], v[160:163]
	ds_read_b128 v[248:251], v255 offset:13888
	s_waitcnt lgkmcnt(4)
	v_mfma_f32_16x16x32_bf16 v[92:95], v[232:235], v[8:11], v[92:95]
	ds_read_b128 v[228:231], v255 offset:128
	s_waitcnt lgkmcnt(4)
	v_mfma_f32_16x16x32_bf16 v[96:99], v[236:239], v[4:7], v[176:179]
	ds_read_b128 v[232:235], v255 offset:192
	s_waitcnt lgkmcnt(4)
	v_mfma_f32_16x16x32_bf16 v[96:99], v[240:243], v[8:11], v[96:99]
	ds_read_b128 v[236:239], v255 offset:4736
	s_waitcnt lgkmcnt(4)
	v_mfma_f32_16x16x32_bf16 v[100:103], v[244:247], v[4:7], v[180:183]
	ds_read_b128 v[240:243], v255 offset:4800
	s_waitcnt lgkmcnt(4)
	v_mfma_f32_16x16x32_bf16 v[100:103], v[248:251], v[8:11], v[100:103]
	ds_read_b128 v[244:247], v255 offset:9344
	s_waitcnt lgkmcnt(4)
	v_mfma_f32_16x16x32_bf16 v[104:107], v[228:231], v[12:15], v[204:207]
	ds_read_b128 v[248:251], v255 offset:9408
	s_waitcnt lgkmcnt(4)
	v_mfma_f32_16x16x32_bf16 v[104:107], v[232:235], v[16:19], v[104:107]
	ds_read_b128 v[228:231], v255 offset:13952
	s_waitcnt lgkmcnt(4)
	v_mfma_f32_16x16x32_bf16 v[108:111], v[236:239], v[12:15], v[208:211]
	ds_read_b128 v[232:235], v255 offset:14016
	s_waitcnt lgkmcnt(4)
	v_mfma_f32_16x16x32_bf16 v[108:111], v[240:243], v[16:19], v[108:111]
	s_waitcnt lgkmcnt(3)
	v_mfma_f32_16x16x32_bf16 v[112:115], v[244:247], v[12:15], v[184:187]
	s_waitcnt lgkmcnt(2)
	v_mfma_f32_16x16x32_bf16 v[112:115], v[248:251], v[16:19], v[112:115]
	s_waitcnt lgkmcnt(1)
	v_mfma_f32_16x16x32_bf16 v[116:119], v[228:231], v[12:15], v[188:191]
	s_waitcnt lgkmcnt(0)
	v_mfma_f32_16x16x32_bf16 v[116:119], v[232:235], v[16:19], v[116:119]
	v_max3_f32 v26, v88, v89, v90
	v_max3_f32 v26, v26, v91, v92
	v_max3_f32 v26, v26, v93, v94
	v_max3_f32 v26, v26, v95, v96
	v_max3_f32 v26, v26, v97, v98
	v_max3_f32 v26, v26, v99, v100
	v_max3_f32 v26, v26, v101, v102
	v_max_f32_e32 v26, v26, v103
	v_cmp_lt_f32_e32 vcc, s66, v26
	s_cbranch_vccz .Ld_nr_A0_0
	v_mov_b32_e32 v27, v26
	s_nop 1
	v_permlane16_swap_b32_e32 v26, v27
	v_max_f32_e32 v26, v26, v27
	v_mov_b32_e32 v27, v26
	s_nop 1
	v_permlane32_swap_b32_e32 v26, v27
	v_max_f32_e32 v26, v26, v27
	v_cmp_lt_f32_e32 vcc, s66, v26
	s_nop 1
	v_cndmask_b32_e32 v3, 0, v26, vcc
	v_sub_f32_e32 v2, 0, v3
	v_min_f32_e32 v2, 0, v2
	v_exp_f32_e32 v2, v2
	v_sub_f32_e32 v24, v24, v3
	v_mul_f32_e32 v0, v0, v2
	v_mul_f32_e32 v28, v28, v2
	v_mul_f32_e32 v29, v29, v2
	v_mul_f32_e32 v30, v30, v2
	v_mul_f32_e32 v31, v31, v2
	v_mul_f32_e32 v32, v32, v2
	v_mul_f32_e32 v33, v33, v2
	v_mul_f32_e32 v34, v34, v2
	v_mul_f32_e32 v35, v35, v2
	v_mul_f32_e32 v40, v40, v2
	v_mul_f32_e32 v41, v41, v2
	v_mul_f32_e32 v42, v42, v2
	v_mul_f32_e32 v43, v43, v2
	v_mul_f32_e32 v52, v52, v2
	v_mul_f32_e32 v53, v53, v2
	v_mul_f32_e32 v54, v54, v2
	v_mul_f32_e32 v55, v55, v2
	v_mul_f32_e32 v56, v56, v2
	v_mul_f32_e32 v57, v57, v2
	v_mul_f32_e32 v58, v58, v2
	v_mul_f32_e32 v59, v59, v2
	v_mul_f32_e32 v64, v64, v2
	v_mul_f32_e32 v65, v65, v2
	v_mul_f32_e32 v66, v66, v2
	v_mul_f32_e32 v67, v67, v2
	v_mul_f32_e32 v72, v72, v2
	v_mul_f32_e32 v73, v73, v2
	v_mul_f32_e32 v74, v74, v2
	v_mul_f32_e32 v75, v75, v2
	v_mul_f32_e32 v84, v84, v2
	v_mul_f32_e32 v85, v85, v2
	v_mul_f32_e32 v86, v86, v2
	v_mul_f32_e32 v87, v87, v2
	v_sub_f32_e32 v88, v88, v3
	v_sub_f32_e32 v89, v89, v3
	v_sub_f32_e32 v90, v90, v3
	v_sub_f32_e32 v91, v91, v3
	v_sub_f32_e32 v92, v92, v3
	v_sub_f32_e32 v93, v93, v3
	v_sub_f32_e32 v94, v94, v3
	v_sub_f32_e32 v95, v95, v3
	v_sub_f32_e32 v96, v96, v3
	v_sub_f32_e32 v97, v97, v3
	v_sub_f32_e32 v98, v98, v3
	v_sub_f32_e32 v99, v99, v3
	v_sub_f32_e32 v100, v100, v3
	v_sub_f32_e32 v101, v101, v3
	v_sub_f32_e32 v102, v102, v3
	v_sub_f32_e32 v103, v103, v3

.Ld_nr_A0_1:
	v_exp_f32_e32 v104, v104
	v_exp_f32_e32 v105, v105
	v_exp_f32_e32 v106, v106
	v_exp_f32_e32 v107, v107
	v_exp_f32_e32 v108, v108
	v_exp_f32_e32 v109, v109
	v_exp_f32_e32 v110, v110
	v_exp_f32_e32 v111, v111
	v_exp_f32_e32 v112, v112
	v_exp_f32_e32 v113, v113
	v_exp_f32_e32 v114, v114
	v_exp_f32_e32 v115, v115
	v_exp_f32_e32 v116, v116
	v_exp_f32_e32 v117, v117
	v_exp_f32_e32 v118, v118
	v_exp_f32_e32 v119, v119
	s_nop 0
	v_add_f32_e32 v26, v104, v105
	v_add_f32_e32 v26, v26, v106
	v_add_f32_e32 v26, v26, v107
	v_add_f32_e32 v26, v26, v108
	v_add_f32_e32 v26, v26, v109
	v_add_f32_e32 v26, v26, v110
	v_add_f32_e32 v26, v26, v111
	v_add_f32_e32 v26, v26, v112
	v_add_f32_e32 v26, v26, v113
	v_add_f32_e32 v26, v26, v114
	v_add_f32_e32 v26, v26, v115
	v_add_f32_e32 v26, v26, v116
	v_add_f32_e32 v26, v26, v117
	v_add_f32_e32 v26, v26, v118
	v_add_f32_e32 v26, v26, v119
	v_add_f32_e32 v151, v151, v26
	v_cvt_pk_bf16_f32 v128, v104, v105
	v_cvt_pk_bf16_f32 v129, v106, v107
	v_cvt_pk_bf16_f32 v130, v108, v109
	v_cvt_pk_bf16_f32 v131, v110, v111
	v_cvt_pk_bf16_f32 v152, v112, v113
	v_cvt_pk_bf16_f32 v153, v114, v115
	v_cvt_pk_bf16_f32 v154, v116, v117
	v_cvt_pk_bf16_f32 v155, v118, v119
	v_add_f32_e32 v165, 0x42800000, v165
	v_mov_b32_e32 v156, v165
	v_add_f32_e32 v157, 0x3f800000, v165
	v_add_f32_e32 v158, 0x40000000, v165
	v_add_f32_e32 v159, 0x40400000, v165
	v_add_f32_e32 v160, 0x41800000, v165
	v_add_f32_e32 v161, 0x41880000, v165
	v_add_f32_e32 v162, 0x41900000, v165
	v_add_f32_e32 v163, 0x41980000, v165
	v_add_f32_e32 v176, 0x42000000, v165
	v_add_f32_e32 v177, 0x42040000, v165
	v_add_f32_e32 v178, 0x42080000, v165
	v_add_f32_e32 v179, 0x420c0000, v165
	v_add_f32_e32 v180, 0x42400000, v165
	v_add_f32_e32 v181, 0x42440000, v165
	v_add_f32_e32 v182, 0x42480000, v165
	v_add_f32_e32 v183, 0x424c0000, v165
	v_fma_f32 v204, -v150, |v156|, v25
	v_fma_f32 v205, -v150, |v157|, v25
	v_fma_f32 v206, -v150, |v158|, v25
	v_fma_f32 v207, -v150, |v159|, v25
	v_fma_f32 v208, -v150, |v160|, v25
	v_fma_f32 v209, -v150, |v161|, v25
	v_fma_f32 v210, -v150, |v162|, v25
	v_fma_f32 v211, -v150, |v163|, v25
	v_fma_f32 v184, -v150, |v176|, v25
	v_fma_f32 v185, -v150, |v177|, v25
	v_fma_f32 v186, -v150, |v178|, v25
	v_fma_f32 v187, -v150, |v179|, v25
	v_fma_f32 v188, -v150, |v180|, v25
	v_fma_f32 v189, -v150, |v181|, v25
	v_fma_f32 v190, -v150, |v182|, v25
	v_fma_f32 v191, -v150, |v183|, v25
	v_fma_f32 v156, -v150, |v156|, v24
	v_fma_f32 v157, -v150, |v157|, v24
	v_fma_f32 v158, -v150, |v158|, v24
	v_fma_f32 v159, -v150, |v159|, v24
	v_fma_f32 v160, -v150, |v160|, v24
	v_fma_f32 v161, -v150, |v161|, v24
	v_fma_f32 v162, -v150, |v162|, v24
	v_fma_f32 v163, -v150, |v163|, v24
	v_fma_f32 v176, -v150, |v176|, v24
	v_fma_f32 v177, -v150, |v177|, v24
	v_fma_f32 v178, -v150, |v178|, v24
	v_fma_f32 v179, -v150, |v179|, v24
	v_fma_f32 v180, -v150, |v180|, v24
	v_fma_f32 v181, -v150, |v181|, v24
	v_fma_f32 v182, -v150, |v182|, v24
	v_fma_f32 v183, -v150, |v183|, v24
	s_waitcnt vmcnt(0)
	ds_write_b128 v169, v[212:215] offset:18432
	ds_write_b128 v169, v[216:219] offset:27648
	ds_write_b128 v164, v[220:223] offset:36864
	ds_write_b128 v164, v[224:227] offset:46080
	s_mov_b32 s31, s38
	s_mov_b32 s38, s39
	s_add_i32 s39, s39, 0x4800
	s_cmp_lg_u32 s39, 0xd800
	s_cselect_b32 s39, s39, 0
	s_mov_b32 s66, 0x42800000
	s_add_i32 s5, s5, 1
	s_min_u32 s8, s5, 62
	s_add_i32 s8, s8, 1
	s_mul_i32 s30, s8, 0xf8000
	s_waitcnt lgkmcnt(0)
	s_barrier
	v_add_u32_e32 v174, s31, v168
	v_add_u32_e32 v164, s39, v169
	s_add_u32 s80, s42, s30
	s_addc_u32 s81, s43, 0
	s_add_u32 s86, s80, 0x7c000
	s_addc_u32 s87, s81, 0
	s_add_u32 s96, s46, s30
	s_addc_u32 s97, s47, 0
	s_add_u32 s98, s96, 0x7c000
	s_addc_u32 s99, s97, 0
	global_load_dwordx4 v[212:215], v173, s[80:81]
	global_load_dwordx4 v[220:223], v175, s[96:97]
	global_load_dwordx4 v[216:219], v173, s[86:87]
	global_load_dwordx4 v[224:227], v175, s[98:99]
	ds_read_b64_tr_b16 v[228:229], v174 offset:36864
	ds_read_b64_tr_b16 v[230:231], v174 offset:41472
	ds_read_b64_tr_b16 v[232:233], v174 offset:36896
	ds_read_b64_tr_b16 v[234:235], v174 offset:41504
	ds_read_b64_tr_b16 v[236:237], v174 offset:36928
	ds_read_b64_tr_b16 v[238:239], v174 offset:41536
	ds_read_b64_tr_b16 v[240:241], v174 offset:36960
	ds_read_b64_tr_b16 v[242:243], v174 offset:41568
	ds_read_b64_tr_b16 v[244:245], v174 offset:36992
	ds_read_b64_tr_b16 v[246:247], v174 offset:41600
	s_waitcnt lgkmcnt(8)
	v_mfma_f32_16x16x32_bf16 v[28:31], v[228:231], v[120:123], v[28:31]
	v_mfma_f32_16x16x32_bf16 v[36:39], v[228:231], v[128:131], v[36:39]
	ds_read_b64_tr_b16 v[248:249], v174 offset:37024
	ds_read_b64_tr_b16 v[250:251], v174 offset:41632
	s_waitcnt lgkmcnt(8)
	v_mfma_f32_16x16x32_bf16 v[32:35], v[232:235], v[120:123], v[32:35]
	v_mfma_f32_16x16x32_bf16 v[44:47], v[232:235], v[128:131], v[44:47]
	ds_read_b64_tr_b16 v[228:229], v174 offset:37056
	ds_read_b64_tr_b16 v[230:231], v174 offset:41664
	s_waitcnt lgkmcnt(8)
	v_mfma_f32_16x16x32_bf16 v[40:43], v[236:239], v[120:123], v[40:43]
	v_mfma_f32_16x16x32_bf16 v[48:51], v[236:239], v[128:131], v[48:51]
	ds_read_b64_tr_b16 v[232:233], v174 offset:37088
	ds_read_b64_tr_b16 v[234:235], v174 offset:41696
	s_waitcnt lgkmcnt(8)
	v_mfma_f32_16x16x32_bf16 v[52:55], v[240:243], v[120:123], v[52:55]
	v_mfma_f32_16x16x32_bf16 v[60:63], v[240:243], v[128:131], v[60:63]
	ds_read_b64_tr_b16 v[236:237], v174 offset:46080
	ds_read_b64_tr_b16 v[238:239], v174 offset:50688
	s_waitcnt lgkmcnt(8)
	v_mfma_f32_16x16x32_bf16 v[56:59], v[244:247], v[120:123], v[56:59]
	v_mfma_f32_16x16x32_bf16 v[68:71], v[244:247], v[128:131], v[68:71]
	ds_read_b64_tr_b16 v[240:241], v174 offset:46112
	ds_read_b64_tr_b16 v[242:243], v174 offset:50720
	s_waitcnt lgkmcnt(8)
	v_mfma_f32_16x16x32_bf16 v[64:67], v[248:251], v[120:123], v[64:67]
	v_mfma_f32_16x16x32_bf16 v[76:79], v[248:251], v[128:131], v[76:79]
	ds_read_b64_tr_b16 v[244:245], v174 offset:46144
	ds_read_b64_tr_b16 v[246:247], v174 offset:50752
	s_waitcnt lgkmcnt(8)
	v_mfma_f32_16x16x32_bf16 v[72:75], v[228:231], v[120:123], v[72:75]
	v_mfma_f32_16x16x32_bf16 v[80:83], v[228:231], v[128:131], v[80:83]
	ds_read_b64_tr_b16 v[248:249], v174 offset:46176
	ds_read_b64_tr_b16 v[250:251], v174 offset:50784
	s_waitcnt lgkmcnt(8)
	v_mfma_f32_16x16x32_bf16 v[84:87], v[232:235], v[120:123], v[84:87]
	v_mfma_f32_16x16x32_bf16 v[20:23], v[232:235], v[128:131], v[20:23]
	ds_read_b64_tr_b16 v[228:229], v174 offset:46208
	ds_read_b64_tr_b16 v[230:231], v174 offset:50816
	s_waitcnt lgkmcnt(8)
	v_mfma_f32_16x16x32_bf16 v[28:31], v[236:239], v[124:127], v[28:31]
	v_mfma_f32_16x16x32_bf16 v[36:39], v[236:239], v[152:155], v[36:39]
	ds_read_b64_tr_b16 v[232:233], v174 offset:46240
	ds_read_b64_tr_b16 v[234:235], v174 offset:50848
	s_waitcnt lgkmcnt(8)
	v_mfma_f32_16x16x32_bf16 v[32:35], v[240:243], v[124:127], v[32:35]
	v_mfma_f32_16x16x32_bf16 v[44:47], v[240:243], v[152:155], v[44:47]
	ds_read_b64_tr_b16 v[236:237], v174 offset:46272
	ds_read_b64_tr_b16 v[238:239], v174 offset:50880
	s_waitcnt lgkmcnt(8)
	v_mfma_f32_16x16x32_bf16 v[40:43], v[244:247], v[124:127], v[40:43]
	v_mfma_f32_16x16x32_bf16 v[48:51], v[244:247], v[152:155], v[48:51]
	ds_read_b64_tr_b16 v[240:241], v174 offset:46304
	ds_read_b64_tr_b16 v[242:243], v174 offset:50912
	s_waitcnt lgkmcnt(8)
	v_mfma_f32_16x16x32_bf16 v[52:55], v[248:251], v[124:127], v[52:55]
	v_mfma_f32_16x16x32_bf16 v[60:63], v[248:251], v[152:155], v[60:63]
	ds_read_b128 v[244:247], v255 offset:18432
	s_waitcnt lgkmcnt(7)
	v_mfma_f32_16x16x32_bf16 v[56:59], v[228:231], v[124:127], v[56:59]
	v_mfma_f32_16x16x32_bf16 v[68:71], v[228:231], v[152:155], v[68:71]
	ds_read_b128 v[248:251], v255 offset:18496
	s_waitcnt lgkmcnt(6)
	v_mfma_f32_16x16x32_bf16 v[64:67], v[232:235], v[124:127], v[64:67]
	v_mfma_f32_16x16x32_bf16 v[76:79], v[232:235], v[152:155], v[76:79]
	ds_read_b128 v[228:231], v255 offset:23040
	s_waitcnt lgkmcnt(5)
	v_mfma_f32_16x16x32_bf16 v[72:75], v[236:239], v[124:127], v[72:75]
	v_mfma_f32_16x16x32_bf16 v[80:83], v[236:239], v[152:155], v[80:83]
	ds_read_b128 v[232:235], v255 offset:23104
	s_waitcnt lgkmcnt(4)
	v_mfma_f32_16x16x32_bf16 v[84:87], v[240:243], v[124:127], v[84:87]
	v_mfma_f32_16x16x32_bf16 v[20:23], v[240:243], v[152:155], v[20:23]
	ds_read_b128 v[236:239], v255 offset:27648
	s_waitcnt lgkmcnt(4)
	v_mfma_f32_16x16x32_bf16 v[88:91], v[244:247], v[4:7], v[156:159]
	ds_read_b128 v[240:243], v255 offset:27712
	s_waitcnt lgkmcnt(4)
	v_mfma_f32_16x16x32_bf16 v[88:91], v[248:251], v[8:11], v[88:91]
	ds_read_b128 v[244:247], v255 offset:32256
	s_waitcnt lgkmcnt(4)
	v_mfma_f32_16x16x32_bf16 v[92:95], v[228:231], v[4:7], v[160:163]
	ds_read_b128 v[248:251], v255 offset:32320
	s_waitcnt lgkmcnt(4)
	v_mfma_f32_16x16x32_bf16 v[92:95], v[232:235], v[8:11], v[92:95]
	ds_read_b128 v[228:231], v255 offset:18560
	s_waitcnt lgkmcnt(4)
	v_mfma_f32_16x16x32_bf16 v[96:99], v[236:239], v[4:7], v[176:179]
	ds_read_b128 v[232:235], v255 offset:18624
	s_waitcnt lgkmcnt(4)
	v_mfma_f32_16x16x32_bf16 v[96:99], v[240:243], v[8:11], v[96:99]
	ds_read_b128 v[236:239], v255 offset:23168
	s_waitcnt lgkmcnt(4)
	v_mfma_f32_16x16x32_bf16 v[100:103], v[244:247], v[4:7], v[180:183]
	ds_read_b128 v[240:243], v255 offset:23232
	s_waitcnt lgkmcnt(4)
	v_mfma_f32_16x16x32_bf16 v[100:103], v[248:251], v[8:11], v[100:103]
	ds_read_b128 v[244:247], v255 offset:27776
	s_waitcnt lgkmcnt(4)
	v_mfma_f32_16x16x32_bf16 v[104:107], v[228:231], v[12:15], v[204:207]
	ds_read_b128 v[248:251], v255 offset:27840
	s_waitcnt lgkmcnt(4)
	v_mfma_f32_16x16x32_bf16 v[104:107], v[232:235], v[16:19], v[104:107]
	ds_read_b128 v[228:231], v255 offset:32384
	s_waitcnt lgkmcnt(4)
	v_mfma_f32_16x16x32_bf16 v[108:111], v[236:239], v[12:15], v[208:211]
	ds_read_b128 v[232:235], v255 offset:32448
	s_waitcnt lgkmcnt(4)
	v_mfma_f32_16x16x32_bf16 v[108:111], v[240:243], v[16:19], v[108:111]
	s_waitcnt lgkmcnt(3)
	v_mfma_f32_16x16x32_bf16 v[112:115], v[244:247], v[12:15], v[184:187]
	s_waitcnt lgkmcnt(2)
	v_mfma_f32_16x16x32_bf16 v[112:115], v[248:251], v[16:19], v[112:115]
	s_waitcnt lgkmcnt(1)
	v_mfma_f32_16x16x32_bf16 v[116:119], v[228:231], v[12:15], v[188:191]
	s_waitcnt lgkmcnt(0)
	v_mfma_f32_16x16x32_bf16 v[116:119], v[232:235], v[16:19], v[116:119]
	v_max3_f32 v26, v88, v89, v90
	v_max3_f32 v26, v26, v91, v92
	v_max3_f32 v26, v26, v93, v94
	v_max3_f32 v26, v26, v95, v96
	v_max3_f32 v26, v26, v97, v98
	v_max3_f32 v26, v26, v99, v100
	v_max3_f32 v26, v26, v101, v102
	v_max_f32_e32 v26, v26, v103
	v_cmp_lt_f32_e32 vcc, s66, v26
	s_cbranch_vccz .Ld_nr_A1_0
	v_mov_b32_e32 v27, v26
	s_nop 1
	v_permlane16_swap_b32_e32 v26, v27
	v_max_f32_e32 v26, v26, v27
	v_mov_b32_e32 v27, v26
	s_nop 1
	v_permlane32_swap_b32_e32 v26, v27
	v_max_f32_e32 v26, v26, v27
	v_cmp_lt_f32_e32 vcc, s66, v26
	s_nop 1
	v_cndmask_b32_e32 v3, 0, v26, vcc
	v_sub_f32_e32 v2, 0, v3
	v_min_f32_e32 v2, 0, v2
	v_exp_f32_e32 v2, v2
	v_sub_f32_e32 v24, v24, v3
	v_mul_f32_e32 v0, v0, v2
	v_mul_f32_e32 v28, v28, v2
	v_mul_f32_e32 v29, v29, v2
	v_mul_f32_e32 v30, v30, v2
	v_mul_f32_e32 v31, v31, v2
	v_mul_f32_e32 v32, v32, v2
	v_mul_f32_e32 v33, v33, v2
	v_mul_f32_e32 v34, v34, v2
	v_mul_f32_e32 v35, v35, v2
	v_mul_f32_e32 v40, v40, v2
	v_mul_f32_e32 v41, v41, v2
	v_mul_f32_e32 v42, v42, v2
	v_mul_f32_e32 v43, v43, v2
	v_mul_f32_e32 v52, v52, v2
	v_mul_f32_e32 v53, v53, v2
	v_mul_f32_e32 v54, v54, v2
	v_mul_f32_e32 v55, v55, v2
	v_mul_f32_e32 v56, v56, v2
	v_mul_f32_e32 v57, v57, v2
	v_mul_f32_e32 v58, v58, v2
	v_mul_f32_e32 v59, v59, v2
	v_mul_f32_e32 v64, v64, v2
	v_mul_f32_e32 v65, v65, v2
	v_mul_f32_e32 v66, v66, v2
	v_mul_f32_e32 v67, v67, v2
	v_mul_f32_e32 v72, v72, v2
	v_mul_f32_e32 v73, v73, v2
	v_mul_f32_e32 v74, v74, v2
	v_mul_f32_e32 v75, v75, v2
	v_mul_f32_e32 v84, v84, v2
	v_mul_f32_e32 v85, v85, v2
	v_mul_f32_e32 v86, v86, v2
	v_mul_f32_e32 v87, v87, v2
	v_sub_f32_e32 v88, v88, v3
	v_sub_f32_e32 v89, v89, v3
	v_sub_f32_e32 v90, v90, v3
	v_sub_f32_e32 v91, v91, v3
	v_sub_f32_e32 v92, v92, v3
	v_sub_f32_e32 v93, v93, v3
	v_sub_f32_e32 v94, v94, v3
	v_sub_f32_e32 v95, v95, v3
	v_sub_f32_e32 v96, v96, v3
	v_sub_f32_e32 v97, v97, v3
	v_sub_f32_e32 v98, v98, v3
	v_sub_f32_e32 v99, v99, v3
	v_sub_f32_e32 v100, v100, v3
	v_sub_f32_e32 v101, v101, v3
	v_sub_f32_e32 v102, v102, v3
	v_sub_f32_e32 v103, v103, v3

.Ld_nr_A1_1:
	v_exp_f32_e32 v104, v104
	v_exp_f32_e32 v105, v105
	v_exp_f32_e32 v106, v106
	v_exp_f32_e32 v107, v107
	v_exp_f32_e32 v108, v108
	v_exp_f32_e32 v109, v109
	v_exp_f32_e32 v110, v110
	v_exp_f32_e32 v111, v111
	v_exp_f32_e32 v112, v112
	v_exp_f32_e32 v113, v113
	v_exp_f32_e32 v114, v114
	v_exp_f32_e32 v115, v115
	v_exp_f32_e32 v116, v116
	v_exp_f32_e32 v117, v117
	v_exp_f32_e32 v118, v118
	v_exp_f32_e32 v119, v119
	s_nop 0
	v_add_f32_e32 v26, v104, v105
	v_add_f32_e32 v26, v26, v106
	v_add_f32_e32 v26, v26, v107
	v_add_f32_e32 v26, v26, v108
	v_add_f32_e32 v26, v26, v109
	v_add_f32_e32 v26, v26, v110
	v_add_f32_e32 v26, v26, v111
	v_add_f32_e32 v26, v26, v112
	v_add_f32_e32 v26, v26, v113
	v_add_f32_e32 v26, v26, v114
	v_add_f32_e32 v26, v26, v115
	v_add_f32_e32 v26, v26, v116
	v_add_f32_e32 v26, v26, v117
	v_add_f32_e32 v26, v26, v118
	v_add_f32_e32 v26, v26, v119
	v_add_f32_e32 v151, v151, v26
	v_cvt_pk_bf16_f32 v128, v104, v105
	v_cvt_pk_bf16_f32 v129, v106, v107
	v_cvt_pk_bf16_f32 v130, v108, v109
	v_cvt_pk_bf16_f32 v131, v110, v111
	v_cvt_pk_bf16_f32 v152, v112, v113
	v_cvt_pk_bf16_f32 v153, v114, v115
	v_cvt_pk_bf16_f32 v154, v116, v117
	v_cvt_pk_bf16_f32 v155, v118, v119
	v_add_f32_e32 v165, 0x42800000, v165
	v_mov_b32_e32 v156, v165
	v_add_f32_e32 v157, 0x3f800000, v165
	v_add_f32_e32 v158, 0x40000000, v165
	v_add_f32_e32 v159, 0x40400000, v165
	v_add_f32_e32 v160, 0x41800000, v165
	v_add_f32_e32 v161, 0x41880000, v165
	v_add_f32_e32 v162, 0x41900000, v165
	v_add_f32_e32 v163, 0x41980000, v165
	v_add_f32_e32 v176, 0x42000000, v165
	v_add_f32_e32 v177, 0x42040000, v165
	v_add_f32_e32 v178, 0x42080000, v165
	v_add_f32_e32 v179, 0x420c0000, v165
	v_add_f32_e32 v180, 0x42400000, v165
	v_add_f32_e32 v181, 0x42440000, v165
	v_add_f32_e32 v182, 0x42480000, v165
	v_add_f32_e32 v183, 0x424c0000, v165
	v_fma_f32 v204, -v150, |v156|, v25
	v_fma_f32 v205, -v150, |v157|, v25
	v_fma_f32 v206, -v150, |v158|, v25
	v_fma_f32 v207, -v150, |v159|, v25
	v_fma_f32 v208, -v150, |v160|, v25
	v_fma_f32 v209, -v150, |v161|, v25
	v_fma_f32 v210, -v150, |v162|, v25
	v_fma_f32 v211, -v150, |v163|, v25
	v_fma_f32 v184, -v150, |v176|, v25
	v_fma_f32 v185, -v150, |v177|, v25
	v_fma_f32 v186, -v150, |v178|, v25
	v_fma_f32 v187, -v150, |v179|, v25
	v_fma_f32 v188, -v150, |v180|, v25
	v_fma_f32 v189, -v150, |v181|, v25
	v_fma_f32 v190, -v150, |v182|, v25
	v_fma_f32 v191, -v150, |v183|, v25
	v_fma_f32 v156, -v150, |v156|, v24
	v_fma_f32 v157, -v150, |v157|, v24
	v_fma_f32 v158, -v150, |v158|, v24
	v_fma_f32 v159, -v150, |v159|, v24
	v_fma_f32 v160, -v150, |v160|, v24
	v_fma_f32 v161, -v150, |v161|, v24
	v_fma_f32 v162, -v150, |v162|, v24
	v_fma_f32 v163, -v150, |v163|, v24
	v_fma_f32 v176, -v150, |v176|, v24
	v_fma_f32 v177, -v150, |v177|, v24
	v_fma_f32 v178, -v150, |v178|, v24
	v_fma_f32 v179, -v150, |v179|, v24
	v_fma_f32 v180, -v150, |v180|, v24
	v_fma_f32 v181, -v150, |v181|, v24
	v_fma_f32 v182, -v150, |v182|, v24
	v_fma_f32 v183, -v150, |v183|, v24
	s_waitcnt vmcnt(0)
	ds_write_b128 v169, v[212:215] offset:0
	ds_write_b128 v169, v[216:219] offset:9216
	ds_write_b128 v164, v[220:223] offset:36864
	ds_write_b128 v164, v[224:227] offset:46080
	s_mov_b32 s31, s38
	s_mov_b32 s38, s39
	s_add_i32 s39, s39, 0x4800
	s_cmp_lg_u32 s39, 0xd800
	s_cselect_b32 s39, s39, 0
	s_mov_b32 s66, 0x42800000
	s_add_i32 s5, s5, 1
	s_min_u32 s8, s5, 62
	s_add_i32 s8, s8, 1
	s_mul_i32 s30, s8, 0xf8000
	s_waitcnt lgkmcnt(0)
	s_barrier
	s_cmp_lt_u32 s5, 64
	s_cbranch_scc1 .Ld_loopA
	v_add_u32_e32 v174, s31, v168
	ds_read_b64_tr_b16 v[228:229], v174 offset:36864
	ds_read_b64_tr_b16 v[230:231], v174 offset:41472
	ds_read_b64_tr_b16 v[232:233], v174 offset:36896
	ds_read_b64_tr_b16 v[234:235], v174 offset:41504
	ds_read_b64_tr_b16 v[236:237], v174 offset:36928
	ds_read_b64_tr_b16 v[238:239], v174 offset:41536
	ds_read_b64_tr_b16 v[240:241], v174 offset:36960
	ds_read_b64_tr_b16 v[242:243], v174 offset:41568
	ds_read_b64_tr_b16 v[244:245], v174 offset:36992
	ds_read_b64_tr_b16 v[246:247], v174 offset:41600
	s_waitcnt lgkmcnt(8)
	v_mfma_f32_16x16x32_bf16 v[28:31], v[228:231], v[120:123], v[28:31]
	v_mfma_f32_16x16x32_bf16 v[36:39], v[228:231], v[128:131], v[36:39]
	ds_read_b64_tr_b16 v[248:249], v174 offset:37024
	ds_read_b64_tr_b16 v[250:251], v174 offset:41632
	s_waitcnt lgkmcnt(8)
	v_mfma_f32_16x16x32_bf16 v[32:35], v[232:235], v[120:123], v[32:35]
	v_mfma_f32_16x16x32_bf16 v[44:47], v[232:235], v[128:131], v[44:47]
	ds_read_b64_tr_b16 v[228:229], v174 offset:37056
	ds_read_b64_tr_b16 v[230:231], v174 offset:41664
	s_waitcnt lgkmcnt(8)
	v_mfma_f32_16x16x32_bf16 v[40:43], v[236:239], v[120:123], v[40:43]
	v_mfma_f32_16x16x32_bf16 v[48:51], v[236:239], v[128:131], v[48:51]
	ds_read_b64_tr_b16 v[232:233], v174 offset:37088
	ds_read_b64_tr_b16 v[234:235], v174 offset:41696
	s_waitcnt lgkmcnt(8)
	v_mfma_f32_16x16x32_bf16 v[52:55], v[240:243], v[120:123], v[52:55]
	v_mfma_f32_16x16x32_bf16 v[60:63], v[240:243], v[128:131], v[60:63]
	ds_read_b64_tr_b16 v[236:237], v174 offset:46080
	ds_read_b64_tr_b16 v[238:239], v174 offset:50688
	s_waitcnt lgkmcnt(8)
	v_mfma_f32_16x16x32_bf16 v[56:59], v[244:247], v[120:123], v[56:59]
	v_mfma_f32_16x16x32_bf16 v[68:71], v[244:247], v[128:131], v[68:71]
	ds_read_b64_tr_b16 v[240:241], v174 offset:46112
	ds_read_b64_tr_b16 v[242:243], v174 offset:50720
	s_waitcnt lgkmcnt(8)
	v_mfma_f32_16x16x32_bf16 v[64:67], v[248:251], v[120:123], v[64:67]
	v_mfma_f32_16x16x32_bf16 v[76:79], v[248:251], v[128:131], v[76:79]
	ds_read_b64_tr_b16 v[244:245], v174 offset:46144
	ds_read_b64_tr_b16 v[246:247], v174 offset:50752
	s_waitcnt lgkmcnt(8)
	v_mfma_f32_16x16x32_bf16 v[72:75], v[228:231], v[120:123], v[72:75]
	v_mfma_f32_16x16x32_bf16 v[80:83], v[228:231], v[128:131], v[80:83]
	ds_read_b64_tr_b16 v[248:249], v174 offset:46176
	ds_read_b64_tr_b16 v[250:251], v174 offset:50784
	s_waitcnt lgkmcnt(8)
	v_mfma_f32_16x16x32_bf16 v[84:87], v[232:235], v[120:123], v[84:87]
	v_mfma_f32_16x16x32_bf16 v[20:23], v[232:235], v[128:131], v[20:23]
	ds_read_b64_tr_b16 v[228:229], v174 offset:46208
	ds_read_b64_tr_b16 v[230:231], v174 offset:50816
	s_waitcnt lgkmcnt(8)
	v_mfma_f32_16x16x32_bf16 v[28:31], v[236:239], v[124:127], v[28:31]
	v_mfma_f32_16x16x32_bf16 v[36:39], v[236:239], v[152:155], v[36:39]
	ds_read_b64_tr_b16 v[232:233], v174 offset:46240
	ds_read_b64_tr_b16 v[234:235], v174 offset:50848
	s_waitcnt lgkmcnt(8)
	v_mfma_f32_16x16x32_bf16 v[32:35], v[240:243], v[124:127], v[32:35]
	v_mfma_f32_16x16x32_bf16 v[44:47], v[240:243], v[152:155], v[44:47]
	ds_read_b64_tr_b16 v[236:237], v174 offset:46272
	ds_read_b64_tr_b16 v[238:239], v174 offset:50880
	s_waitcnt lgkmcnt(8)
	v_mfma_f32_16x16x32_bf16 v[40:43], v[244:247], v[124:127], v[40:43]
	v_mfma_f32_16x16x32_bf16 v[48:51], v[244:247], v[152:155], v[48:51]
	ds_read_b64_tr_b16 v[240:241], v174 offset:46304
	ds_read_b64_tr_b16 v[242:243], v174 offset:50912
	s_waitcnt lgkmcnt(8)
	v_mfma_f32_16x16x32_bf16 v[52:55], v[248:251], v[124:127], v[52:55]
	v_mfma_f32_16x16x32_bf16 v[60:63], v[248:251], v[152:155], v[60:63]
	s_waitcnt lgkmcnt(6)
	v_mfma_f32_16x16x32_bf16 v[56:59], v[228:231], v[124:127], v[56:59]
	v_mfma_f32_16x16x32_bf16 v[68:71], v[228:231], v[152:155], v[68:71]
	s_waitcnt lgkmcnt(4)
	v_mfma_f32_16x16x32_bf16 v[64:67], v[232:235], v[124:127], v[64:67]
	v_mfma_f32_16x16x32_bf16 v[76:79], v[232:235], v[152:155], v[76:79]
	s_waitcnt lgkmcnt(2)
	v_mfma_f32_16x16x32_bf16 v[72:75], v[236:239], v[124:127], v[72:75]
	v_mfma_f32_16x16x32_bf16 v[80:83], v[236:239], v[152:155], v[80:83]
	s_waitcnt lgkmcnt(0)
	v_mfma_f32_16x16x32_bf16 v[84:87], v[240:243], v[124:127], v[84:87]
	v_mfma_f32_16x16x32_bf16 v[20:23], v[240:243], v[152:155], v[20:23]

.LBB0_641:
	s_ashr_i32 s0, s5, 7
	s_mul_i32 s23, s0, 0x3e00000
	s_mul_hi_i32 s17, s0, 0x3e00000
	s_add_u32 s0, s2, s23
	s_addc_u32 s1, s4, s17
	s_lshl_b32 s8, s5, 8
	s_and_b32 s8, s8, 0xf00
	v_and_b32_e32 v32, 15, v2
	v_lshl_add_u32 v0, v0, 5, s8
	s_waitcnt lgkmcnt(0)
	v_or_b32_e32 v3, v0, v32
	v_mov_b64_e32 v[4:5], s[0:1]
	v_mad_i64_i32 v[6:7], s[0:1], v3, s65, v[4:5]
	s_lshl_b32 s0, s5, 3
	v_or_b32_e32 v3, 16, v3
	s_and_b32 s8, s0, 0x380
	v_mad_i64_i32 v[8:9], s[0:1], v3, s65, v[4:5]
	v_ashrrev_i32_e32 v3, 3, v2
	s_waitcnt lgkmcnt(0)
	v_bfe_u32 v33, v2, 4, 2
	v_lshl_add_u64 v[6:7], v[6:7], 0, s[8:9]
	s_mov_b64 s[12:13], 0x1000
	v_lshl_add_u64 v[8:9], v[8:9], 0, s[8:9]
	v_mad_i64_i32 v[4:5], s[0:1], v3, s65, v[4:5]
	v_lshl_add_u64 v[110:111], v[6:7], 0, s[12:13]
	v_lshlrev_b32_e32 v0, 4, v33
	v_lshl_add_u64 v[108:109], v[8:9], 0, s[12:13]
	s_and_b32 s0, s5, 64
	v_lshl_add_u64 v[6:7], v[110:111], 0, v[0:1]
	v_lshl_add_u64 v[28:29], v[108:109], 0, v[0:1]
	s_lshl_b32 s8, s0, 1
	v_lshlrev_b32_e32 v0, 4, v2
	v_and_b32_e32 v0, 0x70, v0
	v_lshl_add_u64 v[4:5], v[4:5], 0, s[8:9]
	v_lshl_add_u64 v[30:31], v[4:5], 0, v[0:1]
	v_add_co_u32_e32 v4, vcc, s71, v30
	v_lshlrev_b32_e32 v118, 2, v33
	s_nop 0
	v_addc_co_u32_e32 v5, vcc, 0, v31, vcc
	global_load_dwordx4 v[20:23], v[4:5], off offset:1024
	global_load_dwordx4 v[24:27], v[4:5], off offset:1280
	global_load_dwordx4 v[16:19], v[6:7], off
	global_load_dwordx4 v[8:11], v[6:7], off offset:64
	global_load_dwordx4 v[12:15], v[28:29], off
	s_nop 0
	global_load_dwordx4 v[4:7], v[28:29], off offset:64
	v_bfe_u32 v29, v2, 2, 2
	v_lshlrev_b32_e32 v28, 3, v2
	v_or_b32_e32 v29, v118, v29
	s_mov_b64 s[18:19], 0x1400
	v_lshlrev_b32_e32 v34, 3, v33
	v_mul_lo_u32 v35, v3, s40
	v_mul_u32_u24_e32 v32, 0x50, v32
	v_and_b32_e32 v28, 24, v28
	v_mul_u32_u24_e32 v29, 0xa0, v29
	v_lshl_add_u64 v[112:113], v[30:31], 0, s[18:19]
	s_mov_b64 s[18:19], 0x1500
	s_mov_b64 s[88:89], 0x1000
	s_mov_b64 s[0:1], -1
	v_lshlrev_b32_e32 v116, 1, v32
	v_add3_u32 v119, 0, v29, v28
	s_cmp_lt_i32 s30, 4
	v_add3_u32 v120, 0, v35, v0
	v_lshl_add_u64 v[114:115], v[30:31], 0, s[18:19]
	v_lshlrev_b32_e32 v0, 1, v34
	s_barrier
	s_waitcnt vmcnt(5)
	ds_write_b128 v120, v[20:23]
	s_waitcnt vmcnt(4)
	ds_write_b128 v120, v[24:27] offset:20480
	s_waitcnt lgkmcnt(0)
	s_barrier
	s_cbranch_scc1 .Lb_groupA
	s_waitcnt vmcnt(0)
	v_mov_b32_e32 v34, 0
	v_mov_b32_e32 v35, 0
	v_mov_b32_e32 v36, 0
	v_mov_b32_e32 v37, 0
	v_mov_b32_e32 v42, 0
	v_mov_b32_e32 v43, 0
	v_mov_b32_e32 v44, 0
	v_mov_b32_e32 v45, 0
	v_mov_b32_e32 v56, 0
	v_mov_b32_e32 v57, 0
	v_mov_b32_e32 v58, 0
	v_mov_b32_e32 v59, 0
	v_mov_b32_e32 v60, 0
	v_mov_b32_e32 v61, 0
	v_mov_b32_e32 v62, 0
	v_mov_b32_e32 v63, 0
	v_mov_b32_e32 v20, 0
	v_mov_b32_e32 v21, 0
	v_mov_b32_e32 v22, 0
	v_mov_b32_e32 v23, 0
	v_mov_b32_e32 v24, 0
	v_mov_b32_e32 v25, 0
	v_mov_b32_e32 v26, 0
	v_mov_b32_e32 v27, 0
	v_mov_b32_e32 v38, 0
	v_mov_b32_e32 v39, 0
	v_mov_b32_e32 v40, 0
	v_mov_b32_e32 v41, 0
	v_mov_b32_e32 v28, 0
	v_mov_b32_e32 v29, 0
	v_mov_b32_e32 v30, 0
	v_mov_b32_e32 v31, 0
	v_mov_b32_e32 v180, 0
	v_mov_b32_e32 v181, 0
	v_mov_b32_e32 v182, 0
	v_mov_b32_e32 v183, 0
	v_mov_b32_e32 v184, 0
	v_mov_b32_e32 v185, 0
	v_mov_b32_e32 v186, 0
	v_mov_b32_e32 v187, 0
	v_mov_b32_e32 v188, 0
	v_mov_b32_e32 v189, 0
	v_mov_b32_e32 v190, 0
	v_mov_b32_e32 v191, 0
	v_mov_b32_e32 v204, 0
	v_mov_b32_e32 v205, 0
	v_mov_b32_e32 v206, 0
	v_mov_b32_e32 v207, 0
	v_mov_b32_e32 v48, 0
	v_mov_b32_e32 v49, 0
	v_mov_b32_e32 v50, 0
	v_mov_b32_e32 v51, 0
	v_mov_b32_e32 v52, 0
	v_mov_b32_e32 v53, 0
	v_mov_b32_e32 v54, 0
	v_mov_b32_e32 v55, 0
	v_mov_b32_e32 v80, 0
	v_mov_b32_e32 v64, 0
	v_add_u32_e32 v75, v116, v0
	v_readfirstlane_b32 s80, v112
	v_readfirstlane_b32 s81, v113
	v_readfirstlane_b32 s86, v114
	v_readfirstlane_b32 s87, v115
	s_nop 3
	v_subrev_u32_e32 v71, s80, v112
	v_subrev_u32_e32 v73, s86, v114
	s_mov_b32 s20, 0
	s_mov_b32 s42, 0
	s_mov_b32 s43, 0
	s_mov_b32 s51, 10240
	s_mov_b32 s30, 0xf8000
	s_mov_b32 s66, 0xff800000
	s_mov_b32 s67, 0xff800000
	v_mov_b32_e32 v88, 0xff800000
	v_mov_b32_e32 v89, 0xff800000
	v_mov_b32_e32 v90, 0xff800000
	v_mov_b32_e32 v91, 0xff800000
	v_mov_b32_e32 v92, 0xff800000
	v_mov_b32_e32 v93, 0xff800000
	v_mov_b32_e32 v94, 0xff800000
	v_mov_b32_e32 v95, 0xff800000
	v_mov_b32_e32 v96, 0xff800000
	v_mov_b32_e32 v97, 0xff800000
	v_mov_b32_e32 v98, 0xff800000
	v_mov_b32_e32 v99, 0xff800000
	v_mov_b32_e32 v100, 0xff800000
	v_mov_b32_e32 v101, 0xff800000
	v_mov_b32_e32 v102, 0xff800000
	v_mov_b32_e32 v103, 0xff800000
	v_mov_b32_e32 v104, 0xff800000
	v_mov_b32_e32 v105, 0xff800000
	v_mov_b32_e32 v106, 0xff800000
	v_mov_b32_e32 v107, 0xff800000
	v_mov_b32_e32 v168, 0xff800000
	v_mov_b32_e32 v169, 0xff800000
	v_mov_b32_e32 v170, 0xff800000
	v_mov_b32_e32 v171, 0xff800000
	v_mov_b32_e32 v172, 0xff800000
	v_mov_b32_e32 v173, 0xff800000
	v_mov_b32_e32 v174, 0xff800000
	v_mov_b32_e32 v175, 0xff800000
	v_mov_b32_e32 v176, 0xff800000
	v_mov_b32_e32 v177, 0xff800000
	v_mov_b32_e32 v178, 0xff800000
	v_mov_b32_e32 v179, 0xff800000
.Lb_loopB:
	v_add_u32_e32 v72, s42, v119
	v_add_u32_e32 v74, s51, v120
	s_add_u32 s96, s80, s30
	s_addc_u32 s97, s81, 0
	s_add_u32 s98, s86, s30
	s_addc_u32 s99, s87, 0
	global_load_dwordx4 v[208:211], v71, s[96:97]
	global_load_dwordx4 v[212:215], v73, s[98:99]
	ds_read_b128 v[216:219], v75 offset:0
	ds_read_b128 v[220:223], v75 offset:64
	ds_read_b128 v[224:227], v75 offset:2560
	ds_read_b128 v[228:231], v75 offset:2624
	v_exp_f32_e32 v236, v88
	v_exp_f32_e32 v237, v89
	v_exp_f32_e32 v238, v90
	v_exp_f32_e32 v239, v91
	v_exp_f32_e32 v240, v92
	v_exp_f32_e32 v241, v93
	v_exp_f32_e32 v242, v94
	v_exp_f32_e32 v243, v95
	v_exp_f32_e32 v244, v96
	v_exp_f32_e32 v245, v97
	v_exp_f32_e32 v246, v98
	v_exp_f32_e32 v247, v99
	v_exp_f32_e32 v248, v100
	v_exp_f32_e32 v249, v101
	v_exp_f32_e32 v250, v102
	v_exp_f32_e32 v251, v103
	s_nop 0
	v_add_f32_e32 v67, v236, v237
	v_add_f32_e32 v67, v67, v238
	v_add_f32_e32 v67, v67, v239
	v_add_f32_e32 v67, v67, v240
	v_add_f32_e32 v67, v67, v241
	v_add_f32_e32 v67, v67, v242
	v_add_f32_e32 v67, v67, v243
	v_add_f32_e32 v67, v67, v244
	v_add_f32_e32 v67, v67, v245
	v_add_f32_e32 v67, v67, v246
	v_add_f32_e32 v67, v67, v247
	v_add_f32_e32 v67, v67, v248
	v_add_f32_e32 v67, v67, v249
	v_add_f32_e32 v67, v67, v250
	v_add_f32_e32 v67, v67, v251
	v_cmp_lt_f32_e32 vcc, s66, v67
	s_cbranch_vccnz .Lb_rare_B0_0

.Lb_back_B0_1:
	v_add_f32_e32 v64, v64, v67
	v_cvt_pk_bf16_f32 v184, v236, v237
	v_cvt_pk_bf16_f32 v185, v238, v239
	v_cvt_pk_bf16_f32 v186, v240, v241
	v_cvt_pk_bf16_f32 v187, v242, v243
	v_cvt_pk_bf16_f32 v204, v244, v245
	v_cvt_pk_bf16_f32 v205, v246, v247
	v_cvt_pk_bf16_f32 v206, v248, v249
	v_cvt_pk_bf16_f32 v207, v250, v251
	ds_read_b128 v[232:235], v75 offset:5120
	s_waitcnt lgkmcnt(4)
	v_mfma_f32_16x16x32_bf16 v[88:91], v[216:219], v[16:19], v[48:51]
	v_mfma_f32_16x16x32_bf16 v[104:107], v[216:219], v[12:15], v[52:55]
	ds_read_b128 v[216:219], v75 offset:5184
	s_waitcnt lgkmcnt(4)
	v_mfma_f32_16x16x32_bf16 v[88:91], v[220:223], v[8:11], v[88:91]
	v_mfma_f32_16x16x32_bf16 v[104:107], v[220:223], v[4:7], v[104:107]
	ds_read_b128 v[220:223], v75 offset:7680
	s_waitcnt lgkmcnt(4)
	v_mfma_f32_16x16x32_bf16 v[92:95], v[224:227], v[16:19], v[48:51]
	v_mfma_f32_16x16x32_bf16 v[168:171], v[224:227], v[12:15], v[52:55]
	ds_read_b128 v[224:227], v75 offset:7744
	s_waitcnt lgkmcnt(4)
	v_mfma_f32_16x16x32_bf16 v[92:95], v[228:231], v[8:11], v[92:95]
	v_mfma_f32_16x16x32_bf16 v[168:171], v[228:231], v[4:7], v[168:171]
	ds_read_b64_tr_b16 v[228:229], v72 offset:20480
	ds_read_b64_tr_b16 v[230:231], v72 offset:23040
	s_waitcnt lgkmcnt(5)
	v_mfma_f32_16x16x32_bf16 v[96:99], v[232:235], v[16:19], v[48:51]
	v_mfma_f32_16x16x32_bf16 v[172:175], v[232:235], v[12:15], v[52:55]
	ds_read_b64_tr_b16 v[232:233], v72 offset:20512
	ds_read_b64_tr_b16 v[234:235], v72 offset:23072
	s_waitcnt lgkmcnt(6)
	v_mfma_f32_16x16x32_bf16 v[96:99], v[216:219], v[8:11], v[96:99]
	v_mfma_f32_16x16x32_bf16 v[172:175], v[216:219], v[4:7], v[172:175]
	ds_read_b64_tr_b16 v[216:217], v72 offset:20544
	ds_read_b64_tr_b16 v[218:219], v72 offset:23104
	s_waitcnt lgkmcnt(7)
	v_mfma_f32_16x16x32_bf16 v[100:103], v[220:223], v[16:19], v[48:51]
	v_mfma_f32_16x16x32_bf16 v[176:179], v[220:223], v[12:15], v[52:55]
	ds_read_b64_tr_b16 v[220:221], v72 offset:20576
	ds_read_b64_tr_b16 v[222:223], v72 offset:23136
	s_waitcnt lgkmcnt(8)
	v_mfma_f32_16x16x32_bf16 v[100:103], v[224:227], v[8:11], v[100:103]
	v_mfma_f32_16x16x32_bf16 v[176:179], v[224:227], v[4:7], v[176:179]
	ds_read_b64_tr_b16 v[224:225], v72 offset:25600
	ds_read_b64_tr_b16 v[226:227], v72 offset:28160
	s_waitcnt lgkmcnt(8)
	v_mfma_f32_16x16x32_bf16 v[34:37], v[228:231], v[180:183], v[34:37]
	v_mfma_f32_16x16x32_bf16 v[20:23], v[228:231], v[184:187], v[20:23]
	ds_read_b64_tr_b16 v[228:229], v72 offset:25632
	ds_read_b64_tr_b16 v[230:231], v72 offset:28192
	s_waitcnt lgkmcnt(8)
	v_mfma_f32_16x16x32_bf16 v[42:45], v[232:235], v[180:183], v[42:45]
	v_mfma_f32_16x16x32_bf16 v[24:27], v[232:235], v[184:187], v[24:27]
	ds_read_b64_tr_b16 v[232:233], v72 offset:25664
	ds_read_b64_tr_b16 v[234:235], v72 offset:28224
	s_waitcnt lgkmcnt(8)
	v_mfma_f32_16x16x32_bf16 v[56:59], v[216:219], v[180:183], v[56:59]
	v_mfma_f32_16x16x32_bf16 v[38:41], v[216:219], v[184:187], v[38:41]
	ds_read_b64_tr_b16 v[216:217], v72 offset:25696
	ds_read_b64_tr_b16 v[218:219], v72 offset:28256
	s_waitcnt lgkmcnt(8)
	v_mfma_f32_16x16x32_bf16 v[60:63], v[220:223], v[180:183], v[60:63]
	v_mfma_f32_16x16x32_bf16 v[28:31], v[220:223], v[184:187], v[28:31]
	s_waitcnt lgkmcnt(6)
	v_mfma_f32_16x16x32_bf16 v[34:37], v[224:227], v[188:191], v[34:37]
	v_mfma_f32_16x16x32_bf16 v[20:23], v[224:227], v[204:207], v[20:23]
	s_waitcnt lgkmcnt(4)
	v_mfma_f32_16x16x32_bf16 v[42:45], v[228:231], v[188:191], v[42:45]
	v_mfma_f32_16x16x32_bf16 v[24:27], v[228:231], v[204:207], v[24:27]
	s_waitcnt lgkmcnt(2)
	v_mfma_f32_16x16x32_bf16 v[56:59], v[232:235], v[188:191], v[56:59]
	v_mfma_f32_16x16x32_bf16 v[38:41], v[232:235], v[204:207], v[38:41]
	s_waitcnt lgkmcnt(0)
	v_mfma_f32_16x16x32_bf16 v[60:63], v[216:219], v[188:191], v[60:63]
	v_mfma_f32_16x16x32_bf16 v[28:31], v[216:219], v[204:207], v[28:31]
	s_mov_b32 s42, s43
	s_mov_b32 s43, s51
	s_add_i32 s51, s51, 10240
	s_cmp_lg_u32 s51, 30720
	s_cselect_b32 s51, s51, 0
	s_min_u32 s8, s20, 61
	s_add_i32 s8, s8, 2
	s_mul_i32 s30, s8, 0xf8000
	s_nop 1
	s_waitcnt vmcnt(0)
	ds_write_b128 v120, v[208:211] offset:10240
	ds_write_b128 v74, v[212:215] offset:20480
	s_mov_b32 s66, 0xff800000
	s_mov_b32 s67, 0xff800000
	s_cmp_ge_u32 s20, 1
	s_cselect_b32 s66, 0x5f800000, s66
	s_cselect_b32 s67, 0x42000000, s67
	s_add_i32 s20, s20, 1
	s_waitcnt lgkmcnt(0)
	s_barrier
	v_add_u32_e32 v72, s42, v119
	v_add_u32_e32 v74, s51, v120
	s_add_u32 s96, s80, s30
	s_addc_u32 s97, s81, 0
	s_add_u32 s98, s86, s30
	s_addc_u32 s99, s87, 0
	global_load_dwordx4 v[208:211], v71, s[96:97]
	global_load_dwordx4 v[212:215], v73, s[98:99]
	ds_read_b128 v[216:219], v75 offset:10240
	ds_read_b128 v[220:223], v75 offset:10304
	ds_read_b128 v[224:227], v75 offset:12800
	ds_read_b128 v[228:231], v75 offset:12864
	v_exp_f32_e32 v236, v88
	v_exp_f32_e32 v237, v89
	v_exp_f32_e32 v238, v90
	v_exp_f32_e32 v239, v91
	v_exp_f32_e32 v240, v92
	v_exp_f32_e32 v241, v93
	v_exp_f32_e32 v242, v94
	v_exp_f32_e32 v243, v95
	v_exp_f32_e32 v244, v96
	v_exp_f32_e32 v245, v97
	v_exp_f32_e32 v246, v98
	v_exp_f32_e32 v247, v99
	v_exp_f32_e32 v248, v100
	v_exp_f32_e32 v249, v101
	v_exp_f32_e32 v250, v102
	v_exp_f32_e32 v251, v103
	s_nop 0
	v_add_f32_e32 v67, v236, v237
	v_add_f32_e32 v67, v67, v238
	v_add_f32_e32 v67, v67, v239
	v_add_f32_e32 v67, v67, v240
	v_add_f32_e32 v67, v67, v241
	v_add_f32_e32 v67, v67, v242
	v_add_f32_e32 v67, v67, v243
	v_add_f32_e32 v67, v67, v244
	v_add_f32_e32 v67, v67, v245
	v_add_f32_e32 v67, v67, v246
	v_add_f32_e32 v67, v67, v247
	v_add_f32_e32 v67, v67, v248
	v_add_f32_e32 v67, v67, v249
	v_add_f32_e32 v67, v67, v250
	v_add_f32_e32 v67, v67, v251
	v_cmp_lt_f32_e32 vcc, s66, v67
	s_cbranch_vccnz .Lb_rare_B1_0

.Lb_back_B1_1:
	v_add_f32_e32 v64, v64, v67
	v_cvt_pk_bf16_f32 v184, v236, v237
	v_cvt_pk_bf16_f32 v185, v238, v239
	v_cvt_pk_bf16_f32 v186, v240, v241
	v_cvt_pk_bf16_f32 v187, v242, v243
	v_cvt_pk_bf16_f32 v204, v244, v245
	v_cvt_pk_bf16_f32 v205, v246, v247
	v_cvt_pk_bf16_f32 v206, v248, v249
	v_cvt_pk_bf16_f32 v207, v250, v251
	ds_read_b128 v[232:235], v75 offset:15360
	s_waitcnt lgkmcnt(4)
	v_mfma_f32_16x16x32_bf16 v[88:91], v[216:219], v[16:19], v[48:51]
	v_mfma_f32_16x16x32_bf16 v[104:107], v[216:219], v[12:15], v[52:55]
	ds_read_b128 v[216:219], v75 offset:15424
	s_waitcnt lgkmcnt(4)
	v_mfma_f32_16x16x32_bf16 v[88:91], v[220:223], v[8:11], v[88:91]
	v_mfma_f32_16x16x32_bf16 v[104:107], v[220:223], v[4:7], v[104:107]
	ds_read_b128 v[220:223], v75 offset:17920
	s_waitcnt lgkmcnt(4)
	v_mfma_f32_16x16x32_bf16 v[92:95], v[224:227], v[16:19], v[48:51]
	v_mfma_f32_16x16x32_bf16 v[168:171], v[224:227], v[12:15], v[52:55]
	ds_read_b128 v[224:227], v75 offset:17984
	s_waitcnt lgkmcnt(4)
	v_mfma_f32_16x16x32_bf16 v[92:95], v[228:231], v[8:11], v[92:95]
	v_mfma_f32_16x16x32_bf16 v[168:171], v[228:231], v[4:7], v[168:171]
	ds_read_b64_tr_b16 v[228:229], v72 offset:20480
	ds_read_b64_tr_b16 v[230:231], v72 offset:23040
	s_waitcnt lgkmcnt(5)
	v_mfma_f32_16x16x32_bf16 v[96:99], v[232:235], v[16:19], v[48:51]
	v_mfma_f32_16x16x32_bf16 v[172:175], v[232:235], v[12:15], v[52:55]
	ds_read_b64_tr_b16 v[232:233], v72 offset:20512
	ds_read_b64_tr_b16 v[234:235], v72 offset:23072
	s_waitcnt lgkmcnt(6)
	v_mfma_f32_16x16x32_bf16 v[96:99], v[216:219], v[8:11], v[96:99]
	v_mfma_f32_16x16x32_bf16 v[172:175], v[216:219], v[4:7], v[172:175]
	ds_read_b64_tr_b16 v[216:217], v72 offset:20544
	ds_read_b64_tr_b16 v[218:219], v72 offset:23104
	s_waitcnt lgkmcnt(7)
	v_mfma_f32_16x16x32_bf16 v[100:103], v[220:223], v[16:19], v[48:51]
	v_mfma_f32_16x16x32_bf16 v[176:179], v[220:223], v[12:15], v[52:55]
	ds_read_b64_tr_b16 v[220:221], v72 offset:20576
	ds_read_b64_tr_b16 v[222:223], v72 offset:23136
	s_waitcnt lgkmcnt(8)
	v_mfma_f32_16x16x32_bf16 v[100:103], v[224:227], v[8:11], v[100:103]
	v_mfma_f32_16x16x32_bf16 v[176:179], v[224:227], v[4:7], v[176:179]
	ds_read_b64_tr_b16 v[224:225], v72 offset:25600
	ds_read_b64_tr_b16 v[226:227], v72 offset:28160
	s_waitcnt lgkmcnt(8)
	v_mfma_f32_16x16x32_bf16 v[34:37], v[228:231], v[180:183], v[34:37]
	v_mfma_f32_16x16x32_bf16 v[20:23], v[228:231], v[184:187], v[20:23]
	ds_read_b64_tr_b16 v[228:229], v72 offset:25632
	ds_read_b64_tr_b16 v[230:231], v72 offset:28192
	s_waitcnt lgkmcnt(8)
	v_mfma_f32_16x16x32_bf16 v[42:45], v[232:235], v[180:183], v[42:45]
	v_mfma_f32_16x16x32_bf16 v[24:27], v[232:235], v[184:187], v[24:27]
	ds_read_b64_tr_b16 v[232:233], v72 offset:25664
	ds_read_b64_tr_b16 v[234:235], v72 offset:28224
	s_waitcnt lgkmcnt(8)
	v_mfma_f32_16x16x32_bf16 v[56:59], v[216:219], v[180:183], v[56:59]
	v_mfma_f32_16x16x32_bf16 v[38:41], v[216:219], v[184:187], v[38:41]
	ds_read_b64_tr_b16 v[216:217], v72 offset:25696
	ds_read_b64_tr_b16 v[218:219], v72 offset:28256
	s_waitcnt lgkmcnt(8)
	v_mfma_f32_16x16x32_bf16 v[60:63], v[220:223], v[180:183], v[60:63]
	v_mfma_f32_16x16x32_bf16 v[28:31], v[220:223], v[184:187], v[28:31]
	s_waitcnt lgkmcnt(6)
	v_mfma_f32_16x16x32_bf16 v[34:37], v[224:227], v[188:191], v[34:37]
	v_mfma_f32_16x16x32_bf16 v[20:23], v[224:227], v[204:207], v[20:23]
	s_waitcnt lgkmcnt(4)
	v_mfma_f32_16x16x32_bf16 v[42:45], v[228:231], v[188:191], v[42:45]
	v_mfma_f32_16x16x32_bf16 v[24:27], v[228:231], v[204:207], v[24:27]
	s_waitcnt lgkmcnt(2)
	v_mfma_f32_16x16x32_bf16 v[56:59], v[232:235], v[188:191], v[56:59]
	v_mfma_f32_16x16x32_bf16 v[38:41], v[232:235], v[204:207], v[38:41]
	s_waitcnt lgkmcnt(0)
	v_mfma_f32_16x16x32_bf16 v[60:63], v[216:219], v[188:191], v[60:63]
	v_mfma_f32_16x16x32_bf16 v[28:31], v[216:219], v[204:207], v[28:31]
	s_mov_b32 s42, s43
	s_mov_b32 s43, s51
	s_add_i32 s51, s51, 10240
	s_cmp_lg_u32 s51, 30720
	s_cselect_b32 s51, s51, 0
	s_min_u32 s8, s20, 61
	s_add_i32 s8, s8, 2
	s_mul_i32 s30, s8, 0xf8000
	s_nop 1
	s_waitcnt vmcnt(0)
	ds_write_b128 v120, v[208:211] offset:0
	ds_write_b128 v74, v[212:215] offset:20480
	s_mov_b32 s66, 0xff800000
	s_mov_b32 s67, 0xff800000
	s_cmp_ge_u32 s20, 1
	s_cselect_b32 s66, 0x5f800000, s66
	s_cselect_b32 s67, 0x42000000, s67
	s_add_i32 s20, s20, 1
	s_waitcnt lgkmcnt(0)
	s_barrier
	s_cmp_lt_u32 s20, 64
	s_cbranch_scc1 .Lb_loopB
	v_add_u32_e32 v72, s42, v119
	ds_read_b64_tr_b16 v[216:217], v72 offset:20480
	ds_read_b64_tr_b16 v[218:219], v72 offset:23040
	ds_read_b64_tr_b16 v[220:221], v72 offset:20512
	ds_read_b64_tr_b16 v[222:223], v72 offset:23072
	ds_read_b64_tr_b16 v[224:225], v72 offset:20544
	ds_read_b64_tr_b16 v[226:227], v72 offset:23104
	ds_read_b64_tr_b16 v[228:229], v72 offset:20576
	ds_read_b64_tr_b16 v[230:231], v72 offset:23136
	v_exp_f32_e32 v236, v88
	v_exp_f32_e32 v237, v89
	v_exp_f32_e32 v238, v90
	v_exp_f32_e32 v239, v91
	v_exp_f32_e32 v240, v92
	v_exp_f32_e32 v241, v93
	v_exp_f32_e32 v242, v94
	v_exp_f32_e32 v243, v95
	v_exp_f32_e32 v244, v96
	v_exp_f32_e32 v245, v97
	v_exp_f32_e32 v246, v98
	v_exp_f32_e32 v247, v99
	v_exp_f32_e32 v248, v100
	v_exp_f32_e32 v249, v101
	v_exp_f32_e32 v250, v102
	v_exp_f32_e32 v251, v103
	s_nop 0
	v_add_f32_e32 v67, v236, v237
	v_add_f32_e32 v67, v67, v238
	v_add_f32_e32 v67, v67, v239
	v_add_f32_e32 v67, v67, v240
	v_add_f32_e32 v67, v67, v241
	v_add_f32_e32 v67, v67, v242
	v_add_f32_e32 v67, v67, v243
	v_add_f32_e32 v67, v67, v244
	v_add_f32_e32 v67, v67, v245
	v_add_f32_e32 v67, v67, v246
	v_add_f32_e32 v67, v67, v247
	v_add_f32_e32 v67, v67, v248
	v_add_f32_e32 v67, v67, v249
	v_add_f32_e32 v67, v67, v250
	v_add_f32_e32 v67, v67, v251
	v_cmp_lt_f32_e32 vcc, s66, v67
	s_cbranch_vccnz .Lb_rare_Bt_0

.Lb_groupA:
	s_waitcnt vmcnt(0)
	v_mov_b32_e32 v34, 0
	v_mov_b32_e32 v35, 0
	v_mov_b32_e32 v36, 0
	v_mov_b32_e32 v37, 0
	v_mov_b32_e32 v42, 0
	v_mov_b32_e32 v43, 0
	v_mov_b32_e32 v44, 0
	v_mov_b32_e32 v45, 0
	v_mov_b32_e32 v56, 0
	v_mov_b32_e32 v57, 0
	v_mov_b32_e32 v58, 0
	v_mov_b32_e32 v59, 0
	v_mov_b32_e32 v60, 0
	v_mov_b32_e32 v61, 0
	v_mov_b32_e32 v62, 0
	v_mov_b32_e32 v63, 0
	v_mov_b32_e32 v20, 0
	v_mov_b32_e32 v21, 0
	v_mov_b32_e32 v22, 0
	v_mov_b32_e32 v23, 0
	v_mov_b32_e32 v24, 0
	v_mov_b32_e32 v25, 0
	v_mov_b32_e32 v26, 0
	v_mov_b32_e32 v27, 0
	v_mov_b32_e32 v38, 0
	v_mov_b32_e32 v39, 0
	v_mov_b32_e32 v40, 0
	v_mov_b32_e32 v41, 0
	v_mov_b32_e32 v28, 0
	v_mov_b32_e32 v29, 0
	v_mov_b32_e32 v30, 0
	v_mov_b32_e32 v31, 0
	v_mov_b32_e32 v180, 0
	v_mov_b32_e32 v181, 0
	v_mov_b32_e32 v182, 0
	v_mov_b32_e32 v183, 0
	v_mov_b32_e32 v184, 0
	v_mov_b32_e32 v185, 0
	v_mov_b32_e32 v186, 0
	v_mov_b32_e32 v187, 0
	v_mov_b32_e32 v188, 0
	v_mov_b32_e32 v189, 0
	v_mov_b32_e32 v190, 0
	v_mov_b32_e32 v191, 0
	v_mov_b32_e32 v204, 0
	v_mov_b32_e32 v205, 0
	v_mov_b32_e32 v206, 0
	v_mov_b32_e32 v207, 0
	v_mov_b32_e32 v48, 0
	v_mov_b32_e32 v49, 0
	v_mov_b32_e32 v50, 0
	v_mov_b32_e32 v51, 0
	v_mov_b32_e32 v52, 0
	v_mov_b32_e32 v53, 0
	v_mov_b32_e32 v54, 0
	v_mov_b32_e32 v55, 0
	v_mov_b32_e32 v80, 0
	v_mov_b32_e32 v64, 0
	v_add_u32_e32 v75, v116, v0
	v_readfirstlane_b32 s80, v112
	v_readfirstlane_b32 s81, v113
	v_readfirstlane_b32 s86, v114
	v_readfirstlane_b32 s87, v115
	s_nop 3
	v_subrev_u32_e32 v71, s80, v112
	v_subrev_u32_e32 v73, s86, v114
	s_mov_b32 s20, 0
	s_mov_b32 s42, 0
	s_mov_b32 s43, 0
	s_mov_b32 s51, 10240
	s_mov_b32 s30, 0xf8000
	s_mov_b32 s66, 0xff800000
	s_mov_b32 s67, 0xff800000
.Lb_loopA:
	v_add_u32_e32 v72, s42, v119
	v_add_u32_e32 v74, s51, v120
	s_add_u32 s96, s80, s30
	s_addc_u32 s97, s81, 0
	s_add_u32 s98, s86, s30
	s_addc_u32 s99, s87, 0
	global_load_dwordx4 v[208:211], v71, s[96:97]
	global_load_dwordx4 v[212:215], v73, s[98:99]
	ds_read_b64_tr_b16 v[216:217], v72 offset:20480
	ds_read_b64_tr_b16 v[218:219], v72 offset:23040
	ds_read_b64_tr_b16 v[220:221], v72 offset:20512
	ds_read_b64_tr_b16 v[222:223], v72 offset:23072
	ds_read_b64_tr_b16 v[224:225], v72 offset:20544
	ds_read_b64_tr_b16 v[226:227], v72 offset:23104
	ds_read_b64_tr_b16 v[228:229], v72 offset:20576
	ds_read_b64_tr_b16 v[230:231], v72 offset:23136
	ds_read_b64_tr_b16 v[232:233], v72 offset:25600
	ds_read_b64_tr_b16 v[234:235], v72 offset:28160
	s_waitcnt lgkmcnt(8)
	v_mfma_f32_16x16x32_bf16 v[34:37], v[216:219], v[180:183], v[34:37]
	v_mfma_f32_16x16x32_bf16 v[20:23], v[216:219], v[184:187], v[20:23]
	ds_read_b64_tr_b16 v[216:217], v72 offset:25632
	ds_read_b64_tr_b16 v[218:219], v72 offset:28192
	s_waitcnt lgkmcnt(8)
	v_mfma_f32_16x16x32_bf16 v[42:45], v[220:223], v[180:183], v[42:45]
	v_mfma_f32_16x16x32_bf16 v[24:27], v[220:223], v[184:187], v[24:27]
	ds_read_b64_tr_b16 v[220:221], v72 offset:25664
	ds_read_b64_tr_b16 v[222:223], v72 offset:28224
	s_waitcnt lgkmcnt(8)
	v_mfma_f32_16x16x32_bf16 v[56:59], v[224:227], v[180:183], v[56:59]
	v_mfma_f32_16x16x32_bf16 v[38:41], v[224:227], v[184:187], v[38:41]
	ds_read_b64_tr_b16 v[224:225], v72 offset:25696
	ds_read_b64_tr_b16 v[226:227], v72 offset:28256
	s_waitcnt lgkmcnt(8)
	v_mfma_f32_16x16x32_bf16 v[60:63], v[228:231], v[180:183], v[60:63]
	v_mfma_f32_16x16x32_bf16 v[28:31], v[228:231], v[184:187], v[28:31]
	ds_read_b128 v[228:231], v75 offset:0
	s_waitcnt lgkmcnt(7)
	v_mfma_f32_16x16x32_bf16 v[34:37], v[232:235], v[188:191], v[34:37]
	v_mfma_f32_16x16x32_bf16 v[20:23], v[232:235], v[204:207], v[20:23]
	ds_read_b128 v[232:235], v75 offset:64
	s_waitcnt lgkmcnt(6)
	v_mfma_f32_16x16x32_bf16 v[42:45], v[216:219], v[188:191], v[42:45]
	v_mfma_f32_16x16x32_bf16 v[24:27], v[216:219], v[204:207], v[24:27]
	ds_read_b128 v[216:219], v75 offset:2560
	s_waitcnt lgkmcnt(5)
	v_mfma_f32_16x16x32_bf16 v[56:59], v[220:223], v[188:191], v[56:59]
	v_mfma_f32_16x16x32_bf16 v[38:41], v[220:223], v[204:207], v[38:41]
	ds_read_b128 v[220:223], v75 offset:2624
	s_waitcnt lgkmcnt(4)
	v_mfma_f32_16x16x32_bf16 v[60:63], v[224:227], v[188:191], v[60:63]
	v_mfma_f32_16x16x32_bf16 v[28:31], v[224:227], v[204:207], v[28:31]
	ds_read_b128 v[224:227], v75 offset:5120
	s_waitcnt lgkmcnt(4)
	v_mfma_f32_16x16x32_bf16 v[88:91], v[228:231], v[16:19], v[48:51]
	v_mfma_f32_16x16x32_bf16 v[104:107], v[228:231], v[12:15], v[52:55]
	ds_read_b128 v[228:231], v75 offset:5184
	s_waitcnt lgkmcnt(4)
	v_mfma_f32_16x16x32_bf16 v[88:91], v[232:235], v[8:11], v[88:91]
	v_mfma_f32_16x16x32_bf16 v[104:107], v[232:235], v[4:7], v[104:107]
	ds_read_b128 v[232:235], v75 offset:7680
	s_waitcnt lgkmcnt(4)
	v_mfma_f32_16x16x32_bf16 v[92:95], v[216:219], v[16:19], v[48:51]
	v_mfma_f32_16x16x32_bf16 v[168:171], v[216:219], v[12:15], v[52:55]
	ds_read_b128 v[216:219], v75 offset:7744
	s_waitcnt lgkmcnt(4)
	v_mfma_f32_16x16x32_bf16 v[92:95], v[220:223], v[8:11], v[92:95]
	v_mfma_f32_16x16x32_bf16 v[168:171], v[220:223], v[4:7], v[168:171]
	s_waitcnt lgkmcnt(3)
	v_mfma_f32_16x16x32_bf16 v[96:99], v[224:227], v[16:19], v[48:51]
	v_mfma_f32_16x16x32_bf16 v[172:175], v[224:227], v[12:15], v[52:55]
	s_waitcnt lgkmcnt(2)
	v_mfma_f32_16x16x32_bf16 v[96:99], v[228:231], v[8:11], v[96:99]
	v_mfma_f32_16x16x32_bf16 v[172:175], v[228:231], v[4:7], v[172:175]
	s_waitcnt lgkmcnt(1)
	v_mfma_f32_16x16x32_bf16 v[100:103], v[232:235], v[16:19], v[48:51]
	v_mfma_f32_16x16x32_bf16 v[176:179], v[232:235], v[12:15], v[52:55]
	s_waitcnt lgkmcnt(0)
	v_mfma_f32_16x16x32_bf16 v[100:103], v[216:219], v[8:11], v[100:103]
	v_mfma_f32_16x16x32_bf16 v[176:179], v[216:219], v[4:7], v[176:179]
	s_mov_b32 s42, s43
	s_mov_b32 s43, s51
	s_add_i32 s51, s51, 10240
	s_cmp_lg_u32 s51, 30720
	s_cselect_b32 s51, s51, 0
	s_min_u32 s8, s20, 61
	s_add_i32 s8, s8, 2
	s_mul_i32 s30, s8, 0xf8000
	s_nop 1
	v_exp_f32_e32 v236, v88
	v_exp_f32_e32 v237, v89
	v_exp_f32_e32 v238, v90
	v_exp_f32_e32 v239, v91
	v_exp_f32_e32 v240, v92
	v_exp_f32_e32 v241, v93
	v_exp_f32_e32 v242, v94
	v_exp_f32_e32 v243, v95
	v_exp_f32_e32 v244, v96
	v_exp_f32_e32 v245, v97
	v_exp_f32_e32 v246, v98
	v_exp_f32_e32 v247, v99
	v_exp_f32_e32 v248, v100
	v_exp_f32_e32 v249, v101
	v_exp_f32_e32 v250, v102
	v_exp_f32_e32 v251, v103
	s_nop 0
	v_add_f32_e32 v67, v236, v237
	v_add_f32_e32 v67, v67, v238
	v_add_f32_e32 v67, v67, v239
	v_add_f32_e32 v67, v67, v240
	v_add_f32_e32 v67, v67, v241
	v_add_f32_e32 v67, v67, v242
	v_add_f32_e32 v67, v67, v243
	v_add_f32_e32 v67, v67, v244
	v_add_f32_e32 v67, v67, v245
	v_add_f32_e32 v67, v67, v246
	v_add_f32_e32 v67, v67, v247
	v_add_f32_e32 v67, v67, v248
	v_add_f32_e32 v67, v67, v249
	v_add_f32_e32 v67, v67, v250
	v_add_f32_e32 v67, v67, v251
	v_cmp_lt_f32_e32 vcc, s66, v67
	s_cbranch_vccnz .Lb_rare_A0_0

.Lb_back_A0_1:
	v_add_f32_e32 v64, v64, v67
	v_cvt_pk_bf16_f32 v184, v236, v237
	v_cvt_pk_bf16_f32 v185, v238, v239
	v_cvt_pk_bf16_f32 v186, v240, v241
	v_cvt_pk_bf16_f32 v187, v242, v243
	v_cvt_pk_bf16_f32 v204, v244, v245
	v_cvt_pk_bf16_f32 v205, v246, v247
	v_cvt_pk_bf16_f32 v206, v248, v249
	v_cvt_pk_bf16_f32 v207, v250, v251
	s_waitcnt vmcnt(0)
	ds_write_b128 v120, v[208:211] offset:10240
	ds_write_b128 v74, v[212:215] offset:20480
	s_mov_b32 s66, 0x5f800000
	s_mov_b32 s67, 0x42000000
	s_add_i32 s20, s20, 1
	s_waitcnt lgkmcnt(0)
	s_barrier
	v_add_u32_e32 v72, s42, v119
	v_add_u32_e32 v74, s51, v120
	s_add_u32 s96, s80, s30
	s_addc_u32 s97, s81, 0
	s_add_u32 s98, s86, s30
	s_addc_u32 s99, s87, 0
	global_load_dwordx4 v[208:211], v71, s[96:97]
	global_load_dwordx4 v[212:215], v73, s[98:99]
	ds_read_b64_tr_b16 v[216:217], v72 offset:20480
	ds_read_b64_tr_b16 v[218:219], v72 offset:23040
	ds_read_b64_tr_b16 v[220:221], v72 offset:20512
	ds_read_b64_tr_b16 v[222:223], v72 offset:23072
	ds_read_b64_tr_b16 v[224:225], v72 offset:20544
	ds_read_b64_tr_b16 v[226:227], v72 offset:23104
	ds_read_b64_tr_b16 v[228:229], v72 offset:20576
	ds_read_b64_tr_b16 v[230:231], v72 offset:23136
	ds_read_b64_tr_b16 v[232:233], v72 offset:25600
	ds_read_b64_tr_b16 v[234:235], v72 offset:28160
	s_waitcnt lgkmcnt(8)
	v_mfma_f32_16x16x32_bf16 v[34:37], v[216:219], v[180:183], v[34:37]
	v_mfma_f32_16x16x32_bf16 v[20:23], v[216:219], v[184:187], v[20:23]
	ds_read_b64_tr_b16 v[216:217], v72 offset:25632
	ds_read_b64_tr_b16 v[218:219], v72 offset:28192
	s_waitcnt lgkmcnt(8)
	v_mfma_f32_16x16x32_bf16 v[42:45], v[220:223], v[180:183], v[42:45]
	v_mfma_f32_16x16x32_bf16 v[24:27], v[220:223], v[184:187], v[24:27]
	ds_read_b64_tr_b16 v[220:221], v72 offset:25664
	ds_read_b64_tr_b16 v[222:223], v72 offset:28224
	s_waitcnt lgkmcnt(8)
	v_mfma_f32_16x16x32_bf16 v[56:59], v[224:227], v[180:183], v[56:59]
	v_mfma_f32_16x16x32_bf16 v[38:41], v[224:227], v[184:187], v[38:41]
	ds_read_b64_tr_b16 v[224:225], v72 offset:25696
	ds_read_b64_tr_b16 v[226:227], v72 offset:28256
	s_waitcnt lgkmcnt(8)
	v_mfma_f32_16x16x32_bf16 v[60:63], v[228:231], v[180:183], v[60:63]
	v_mfma_f32_16x16x32_bf16 v[28:31], v[228:231], v[184:187], v[28:31]
	ds_read_b128 v[228:231], v75 offset:10240
	s_waitcnt lgkmcnt(7)
	v_mfma_f32_16x16x32_bf16 v[34:37], v[232:235], v[188:191], v[34:37]
	v_mfma_f32_16x16x32_bf16 v[20:23], v[232:235], v[204:207], v[20:23]
	ds_read_b128 v[232:235], v75 offset:10304
	s_waitcnt lgkmcnt(6)
	v_mfma_f32_16x16x32_bf16 v[42:45], v[216:219], v[188:191], v[42:45]
	v_mfma_f32_16x16x32_bf16 v[24:27], v[216:219], v[204:207], v[24:27]
	ds_read_b128 v[216:219], v75 offset:12800
	s_waitcnt lgkmcnt(5)
	v_mfma_f32_16x16x32_bf16 v[56:59], v[220:223], v[188:191], v[56:59]
	v_mfma_f32_16x16x32_bf16 v[38:41], v[220:223], v[204:207], v[38:41]
	ds_read_b128 v[220:223], v75 offset:12864
	s_waitcnt lgkmcnt(4)
	v_mfma_f32_16x16x32_bf16 v[60:63], v[224:227], v[188:191], v[60:63]
	v_mfma_f32_16x16x32_bf16 v[28:31], v[224:227], v[204:207], v[28:31]
	ds_read_b128 v[224:227], v75 offset:15360
	s_waitcnt lgkmcnt(4)
	v_mfma_f32_16x16x32_bf16 v[88:91], v[228:231], v[16:19], v[48:51]
	v_mfma_f32_16x16x32_bf16 v[104:107], v[228:231], v[12:15], v[52:55]
	ds_read_b128 v[228:231], v75 offset:15424
	s_waitcnt lgkmcnt(4)
	v_mfma_f32_16x16x32_bf16 v[88:91], v[232:235], v[8:11], v[88:91]
	v_mfma_f32_16x16x32_bf16 v[104:107], v[232:235], v[4:7], v[104:107]
	ds_read_b128 v[232:235], v75 offset:17920
	s_waitcnt lgkmcnt(4)
	v_mfma_f32_16x16x32_bf16 v[92:95], v[216:219], v[16:19], v[48:51]
	v_mfma_f32_16x16x32_bf16 v[168:171], v[216:219], v[12:15], v[52:55]
	ds_read_b128 v[216:219], v75 offset:17984
	s_waitcnt lgkmcnt(4)
	v_mfma_f32_16x16x32_bf16 v[92:95], v[220:223], v[8:11], v[92:95]
	v_mfma_f32_16x16x32_bf16 v[168:171], v[220:223], v[4:7], v[168:171]
	s_waitcnt lgkmcnt(3)
	v_mfma_f32_16x16x32_bf16 v[96:99], v[224:227], v[16:19], v[48:51]
	v_mfma_f32_16x16x32_bf16 v[172:175], v[224:227], v[12:15], v[52:55]
	s_waitcnt lgkmcnt(2)
	v_mfma_f32_16x16x32_bf16 v[96:99], v[228:231], v[8:11], v[96:99]
	v_mfma_f32_16x16x32_bf16 v[172:175], v[228:231], v[4:7], v[172:175]
	s_waitcnt lgkmcnt(1)
	v_mfma_f32_16x16x32_bf16 v[100:103], v[232:235], v[16:19], v[48:51]
	v_mfma_f32_16x16x32_bf16 v[176:179], v[232:235], v[12:15], v[52:55]
	s_waitcnt lgkmcnt(0)
	v_mfma_f32_16x16x32_bf16 v[100:103], v[216:219], v[8:11], v[100:103]
	v_mfma_f32_16x16x32_bf16 v[176:179], v[216:219], v[4:7], v[176:179]
	s_mov_b32 s42, s43
	s_mov_b32 s43, s51
	s_add_i32 s51, s51, 10240
	s_cmp_lg_u32 s51, 30720
	s_cselect_b32 s51, s51, 0
	s_min_u32 s8, s20, 61
	s_add_i32 s8, s8, 2
	s_mul_i32 s30, s8, 0xf8000
	s_nop 1
	v_exp_f32_e32 v236, v88
	v_exp_f32_e32 v237, v89
	v_exp_f32_e32 v238, v90
	v_exp_f32_e32 v239, v91
	v_exp_f32_e32 v240, v92
	v_exp_f32_e32 v241, v93
	v_exp_f32_e32 v242, v94
	v_exp_f32_e32 v243, v95
	v_exp_f32_e32 v244, v96
	v_exp_f32_e32 v245, v97
	v_exp_f32_e32 v246, v98
	v_exp_f32_e32 v247, v99
	v_exp_f32_e32 v248, v100
	v_exp_f32_e32 v249, v101
	v_exp_f32_e32 v250, v102
	v_exp_f32_e32 v251, v103
	s_nop 0
	v_add_f32_e32 v67, v236, v237
	v_add_f32_e32 v67, v67, v238
	v_add_f32_e32 v67, v67, v239
	v_add_f32_e32 v67, v67, v240
	v_add_f32_e32 v67, v67, v241
	v_add_f32_e32 v67, v67, v242
	v_add_f32_e32 v67, v67, v243
	v_add_f32_e32 v67, v67, v244
	v_add_f32_e32 v67, v67, v245
	v_add_f32_e32 v67, v67, v246
	v_add_f32_e32 v67, v67, v247
	v_add_f32_e32 v67, v67, v248
	v_add_f32_e32 v67, v67, v249
	v_add_f32_e32 v67, v67, v250
	v_add_f32_e32 v67, v67, v251
	v_cmp_lt_f32_e32 vcc, s66, v67
	s_cbranch_vccnz .Lb_rare_A1_0

.Lb_back_A1_1:
	v_add_f32_e32 v64, v64, v67
	v_cvt_pk_bf16_f32 v184, v236, v237
	v_cvt_pk_bf16_f32 v185, v238, v239
	v_cvt_pk_bf16_f32 v186, v240, v241
	v_cvt_pk_bf16_f32 v187, v242, v243
	v_cvt_pk_bf16_f32 v204, v244, v245
	v_cvt_pk_bf16_f32 v205, v246, v247
	v_cvt_pk_bf16_f32 v206, v248, v249
	v_cvt_pk_bf16_f32 v207, v250, v251
	s_waitcnt vmcnt(0)
	ds_write_b128 v120, v[208:211] offset:0
	ds_write_b128 v74, v[212:215] offset:20480
	s_mov_b32 s66, 0x5f800000
	s_mov_b32 s67, 0x42000000
	s_add_i32 s20, s20, 1
	s_waitcnt lgkmcnt(0)
	s_barrier
	s_cmp_lt_u32 s20, 64
	s_cbranch_scc1 .Lb_loopA
	v_add_u32_e32 v72, s42, v119
	ds_read_b64_tr_b16 v[216:217], v72 offset:20480
	ds_read_b64_tr_b16 v[218:219], v72 offset:23040
	ds_read_b64_tr_b16 v[220:221], v72 offset:20512
	ds_read_b64_tr_b16 v[222:223], v72 offset:23072
	ds_read_b64_tr_b16 v[224:225], v72 offset:20544
	ds_read_b64_tr_b16 v[226:227], v72 offset:23104
	ds_read_b64_tr_b16 v[228:229], v72 offset:20576
	ds_read_b64_tr_b16 v[230:231], v72 offset:23136
	ds_read_b64_tr_b16 v[232:233], v72 offset:25600
	ds_read_b64_tr_b16 v[234:235], v72 offset:28160
	s_waitcnt lgkmcnt(8)
	v_mfma_f32_16x16x32_bf16 v[34:37], v[216:219], v[180:183], v[34:37]
	v_mfma_f32_16x16x32_bf16 v[20:23], v[216:219], v[184:187], v[20:23]
	ds_read_b64_tr_b16 v[216:217], v72 offset:25632
	ds_read_b64_tr_b16 v[218:219], v72 offset:28192
	s_waitcnt lgkmcnt(8)
	v_mfma_f32_16x16x32_bf16 v[42:45], v[220:223], v[180:183], v[42:45]
	v_mfma_f32_16x16x32_bf16 v[24:27], v[220:223], v[184:187], v[24:27]
	ds_read_b64_tr_b16 v[220:221], v72 offset:25664
	ds_read_b64_tr_b16 v[222:223], v72 offset:28224
	s_waitcnt lgkmcnt(8)
	v_mfma_f32_16x16x32_bf16 v[56:59], v[224:227], v[180:183], v[56:59]
	v_mfma_f32_16x16x32_bf16 v[38:41], v[224:227], v[184:187], v[38:41]
	ds_read_b64_tr_b16 v[224:225], v72 offset:25696
	ds_read_b64_tr_b16 v[226:227], v72 offset:28256
	s_waitcnt lgkmcnt(8)
	v_mfma_f32_16x16x32_bf16 v[60:63], v[228:231], v[180:183], v[60:63]
	v_mfma_f32_16x16x32_bf16 v[28:31], v[228:231], v[184:187], v[28:31]
	s_waitcnt lgkmcnt(6)
	v_mfma_f32_16x16x32_bf16 v[34:37], v[232:235], v[188:191], v[34:37]
	v_mfma_f32_16x16x32_bf16 v[20:23], v[232:235], v[204:207], v[20:23]
	s_waitcnt lgkmcnt(4)
	v_mfma_f32_16x16x32_bf16 v[42:45], v[216:219], v[188:191], v[42:45]
	v_mfma_f32_16x16x32_bf16 v[24:27], v[216:219], v[204:207], v[24:27]
	s_waitcnt lgkmcnt(2)
	v_mfma_f32_16x16x32_bf16 v[56:59], v[220:223], v[188:191], v[56:59]
	v_mfma_f32_16x16x32_bf16 v[38:41], v[220:223], v[204:207], v[38:41]
	s_waitcnt lgkmcnt(0)
	v_mfma_f32_16x16x32_bf16 v[60:63], v[224:227], v[188:191], v[60:63]
	v_mfma_f32_16x16x32_bf16 v[28:31], v[224:227], v[204:207], v[28:31]
